# cumsum first stage: LDS reads batched (16/8 serialized LDS round trips -> 1), on top of batched gate loads
# speedup vs baseline: 1.0013x; 1.0013x over previous
; template <int TYPE>
; __device__ __forceinline__ LgRaw lg_issue(const bf16_t* u, int h, int dir, size_t tok0, int tid) {
;     LgRaw r;
;     if constexpr (TYPE == 1) {
;         const int i0 = tid >> 4, d8 = tid & 15, col = (dir ? C_HFB : C_HFF) + h * 128 + d8 * 8;
;         r.a0 = *(const bf16x8*)(u + (tok0 + i0) * DINP + col); r.a1 = *(const bf16x8*)(u + (tok0 + 32 + i0) * DINP + col); r.k = r.a0;
;     } else {
;         const int i = tid >> 3, d8 = tid & 7; const bf16_t* ur = u + (tok0 + i) * DINP;
;         r.a0 = *(const bf16x8*)(ur + (dir ? C_GAB : C_GAF)); r.a1 = *(const bf16x8*)(ur + (dir ? C_GAB : C_GAF) + 8); r.k = *(const bf16x8*)(ur + C_GK + h * 64 + d8 * 8);
;     }
;     return r;
; }
; template <int TYPE>
; __device__ __forceinline__ void lg_compute(const KArgs& a, unsigned char* wsb, int l, int h, int dir, const LgRaw& raw, LAS unsigned char* lds, int tid) {
;     using C = Cfg<TYPE>;
;     LAS float* G = (LAS float*)(lds + SC_G); LAS bf16_t* Kb = (LAS bf16_t*)(lds + SC_K);
;     if constexpr (TYPE == 1) {
;         const float* lbp = (const float*)(wsb + WS_LB) + (dir * DEPTH + l) * 512 + h * 128;
;         const int d8 = tid & 15;
;         const f32x4 lb0 = *(const f32x4*)(lbp + d8 * 8), lb1 = *(const f32x4*)(lbp + d8 * 8 + 4);
;         const float lb[8] = {lb0[0], lb0[1], lb0[2], lb0[3], lb1[0], lb1[1], lb1[2], lb1[3]};
; #pragma unroll
;         for (int e2 = 0; e2 < 2; ++e2) { const int i = (tid >> 4) + 32 * e2;
;             float z[8], lg[8], kk[8]; unpack8(e2 ? raw.a1 : raw.a0, z);
; #pragma unroll
;             for (int e = 0; e < 8; ++e) { const float sg = sigmoid_(fmaxf(z[e], -80.f)); lg[e] = __logf(lb[e] + (1.f - lb[e]) * sg); kk[e] = (1.f - lb[e]) * (1.f - sg); }
;             *(LAS f32x4*)(G + i * C::LDG + d8 * 8) = (f32x4){lg[0], lg[1], lg[2], lg[3]}; *(LAS f32x4*)(G + i * C::LDG + d8 * 8 + 4) = (f32x4){lg[4], lg[5], lg[6], lg[7]};
;             *(LAS bf16x8*)(Kb + i * C::LDK_ + d8 * 8) = pack8(kk); }
; template <int TYPE>
; __device__ __forceinline__ void pass1_item(const KArgs& a, int l, int item, LAS unsigned char* lds) {
;     unsigned char* const wsb = opq(a.ws);
;     const int tid = opaque_tid();
;     using C = Cfg<TYPE>; constexpr int DK = C::DK;
;     const int c = item & (NCH - 1), dir = (item >> 8) & 1, h = (item >> 9) & 3, b = item >> 11;
;     const size_t tok0 = (size_t)b * T + (size_t)c * 64;
.LBB0_265:
	s_ashr_i32 s4, s15, 11
	s_ashr_i32 s5, s4, 31
	s_lshl_b64 s[4:5], s[4:5], 14
	s_and_b32 s6, s14, 0x3fc0
	s_mov_b64 s[12:13], s[68:69]
	s_bfe_i32 s24, s15, 0x10008
	s_bfe_u32 s16, s15, 0x10008
	s_or_b32 s4, s4, s6
	s_add_u32 s6, s12, 0xe300000
	s_addc_u32 s7, s13, 0
	s_lshr_b32 s17, s15, 2
	s_and_b32 s31, s17, 0x180
	v_mov_b32_e32 v12, v195
	s_cmp_eq_u32 s16, 0
	s_cselect_b64 vcc, -1, 0
	v_ashrrev_i32_e32 v8, 4, v12
	s_and_b64 s[18:19], vcc, exec
	s_movk_i32 s17, 0x820
	v_ashrrev_i32_e32 v9, 31, v8
	s_cselect_b32 s34, s17, 0xa20
	v_lshl_add_u64 v[0:1], s[4:5], 0, v[8:9]
	v_mov_b64_e32 v[2:3], s[6:7]
	s_cselect_b32 s30, 1, 14
	s_cselect_b32 s29, 2, 13
	s_cselect_b32 s28, 3, 12
	s_cselect_b32 s27, 4, 11
	s_cselect_b32 s26, 5, 10
	s_cselect_b32 s25, 6, 9
	s_cselect_b32 s23, 9, 6
	s_cselect_b32 s22, 10, 5
	s_cselect_b32 s21, 11, 4
	s_cselect_b32 s20, 12, 3
	s_cselect_b32 s19, 13, 2
	s_cselect_b32 s18, 14, 1
	s_cselect_b32 s17, 15, 0
	s_or_b32 s36, s34, s31
	v_mad_u64_u32 v[2:3], s[34:35], v0, s2, v[2:3]
	s_mulk_i32 s5, 0x2a00
	s_mul_hi_u32 s34, s4, 0x2a00
	s_add_i32 s34, s34, s5
	s_mulk_i32 s4, 0x2a00
	s_add_u32 s4, s6, s4
	s_addc_u32 s5, s7, s34
	s_lshl_b32 s6, s31, 1
	s_add_u32 s4, s4, s6
	s_addc_u32 s5, s5, 0
	v_lshlrev_b32_e32 v13, 3, v12
	s_add_u32 s4, s4, 0x1840
	v_and_b32_e32 v35, 0x78, v13
	s_addc_u32 s5, s5, 0
	v_mad_i32_i24 v3, v1, s2, v3
	v_add_lshl_u32 v112, s36, v35, 1
	v_mov_b64_e32 v[0:1], s[4:5]
	v_lshl_add_u64 v[10:11], v[2:3], 0, v[112:113]
	v_mad_i64_i32 v[2:3], s[4:5], v8, s2, v[0:1]
	v_lshlrev_b32_e32 v112, 1, v35
	v_lshl_add_u64 v[26:27], v[2:3], 0, v[112:113]
	v_add_u32_e32 v2, 32, v8
	v_mad_i64_i32 v[0:1], s[4:5], v2, s2, v[0:1]
	s_lshl_b32 s4, s16, 10
	s_or_b32 s72, s4, s56
	s_lshl_b64 s[4:5], s[72:73], 2
	s_add_u32 s4, s12, s4
	s_addc_u32 s5, s13, s5
	s_lshl_b32 s6, s31, 2
	s_add_u32 s4, s4, s6
	s_addc_u32 s5, s5, 0
	v_lshlrev_b32_e32 v14, 2, v35
	v_mov_b32_e32 v15, v113
	v_lshl_add_u64 v[30:31], v[0:1], 0, v[112:113]
	v_lshl_add_u64 v[0:1], s[4:5], 0, v[14:15]
	s_mov_b64 s[4:5], 0x3e200000
	v_lshl_add_u64 v[2:3], v[0:1], 0, s[4:5]
	s_mov_b32 s4, 0x3e200000
	v_add_co_u32_e64 v0, s[4:5], s4, v0
	s_waitcnt lgkmcnt(0)
	s_nop 0
	v_addc_co_u32_e64 v1, s[4:5], 0, v1, s[4:5]
	s_barrier
	global_load_dwordx4 v[4:7], v[0:1], off
	s_nop 0
	global_load_dwordx4 v[0:3], v[2:3], off offset:16
	v_add_u32_e32 v22, 0, v14
	global_load_dwordx4 v[14:17], v[10:11], off
	v_sub_u32_e32 v34, v22, v112
	s_movk_i32 s0, 0xff81
	s_waitcnt vmcnt(0) lgkmcnt(0)
	v_pk_add_f32 v[36:37], v[4:5], 1.0 op_sel_hi:[1,0] neg_lo:[1,0] neg_hi:[1,0]
	v_pk_add_f32 v[40:41], v[6:7], 1.0 op_sel_hi:[1,0] neg_lo:[1,0] neg_hi:[1,0]
	v_pk_add_f32 v[44:45], v[0:1], 1.0 op_sel_hi:[1,0] neg_lo:[1,0] neg_hi:[1,0]
	v_lshlrev_b32_e32 v9, 16, v14
	v_max_f32_e32 v9, v9, v9
	v_max_f32_e32 v9, 0xc2a00000, v9
	v_mul_f32_e32 v9, 0xbfb8aa3b, v9
	v_exp_f32_e32 v9, v9
	v_and_b32_e32 v14, 0xffff0000, v14
	v_lshlrev_b32_e32 v23, 16, v16
	v_and_b32_e32 v24, 0xffff0000, v16
	v_add_f32_e32 v9, 1.0, v9
	v_rcp_f32_e32 v16, v9
	v_max_f32_e32 v9, v14, v14
	v_max_f32_e32 v9, 0xc2a00000, v9
	v_mul_f32_e32 v9, 0xbfb8aa3b, v9
	v_exp_f32_e32 v9, v9
	v_lshlrev_b32_e32 v28, 16, v17
	v_and_b32_e32 v29, 0xffff0000, v17
	v_lshlrev_b32_e32 v20, 16, v15
	v_add_f32_e32 v9, 1.0, v9
	v_rcp_f32_e32 v17, v9
	v_fma_f32 v9, v36, v16, v4
	v_cmp_gt_f32_e64 s[4:5], s33, v9
	v_and_b32_e32 v21, 0xffff0000, v15
	v_pk_add_f32 v[18:19], v[16:17], 1.0 op_sel_hi:[1,0] neg_lo:[1,0] neg_hi:[1,0]
	v_cndmask_b32_e64 v14, 0, 32, s[4:5]
	v_ldexp_f32 v9, v9, v14
	v_log_f32_e32 v9, v9
	v_pk_mul_f32 v[38:39], v[36:37], v[18:19]
	v_pk_add_f32 v[48:49], v[2:3], 1.0 op_sel_hi:[1,0] neg_lo:[1,0] neg_hi:[1,0]
	v_mul_f32_e32 v14, 0x3f317217, v9
	v_fma_f32 v14, v9, s92, -v14
	v_fmac_f32_e32 v14, 0x3377d1cf, v9
	v_fmac_f32_e32 v14, 0x3f317217, v9
	v_cmp_lt_f32_e64 s[6:7], |v9|, s90
	s_nop 1
	v_cndmask_b32_e64 v9, v9, v14, s[6:7]
	v_cndmask_b32_e64 v14, 0, v238, s[4:5]
	v_sub_f32_e32 v14, v9, v14
	v_fma_f32 v9, v37, v17, v5
	v_cmp_gt_f32_e64 s[4:5], s33, v9
	s_nop 1
	v_cndmask_b32_e64 v15, 0, 32, s[4:5]
	v_ldexp_f32 v9, v9, v15
	v_log_f32_e32 v9, v9
	s_nop 0
	v_mul_f32_e32 v15, 0x3f317217, v9
	v_fma_f32 v15, v9, s92, -v15
	v_fmac_f32_e32 v15, 0x3377d1cf, v9
	v_fmac_f32_e32 v15, 0x3f317217, v9
	v_cmp_lt_f32_e64 s[6:7], |v9|, s90
	s_nop 1
	v_cndmask_b32_e64 v9, v9, v15, s[6:7]
	v_cndmask_b32_e64 v15, 0, v238, s[4:5]
	v_sub_f32_e32 v15, v9, v15
	v_max_f32_e32 v9, v20, v20
	v_max_f32_e32 v9, 0xc2a00000, v9
	v_mul_f32_e32 v9, 0xbfb8aa3b, v9
	v_exp_f32_e32 v9, v9
	s_nop 0
	v_add_f32_e32 v9, 1.0, v9
	v_rcp_f32_e32 v18, v9
	v_max_f32_e32 v9, v21, v21
	v_max_f32_e32 v9, 0xc2a00000, v9
	v_mul_f32_e32 v9, 0xbfb8aa3b, v9
	v_exp_f32_e32 v9, v9
	s_nop 0
	v_add_f32_e32 v9, 1.0, v9
	v_rcp_f32_e32 v19, v9
	v_fma_f32 v9, v40, v18, v6
	v_cmp_gt_f32_e64 s[4:5], s33, v9
	v_pk_add_f32 v[20:21], v[18:19], 1.0 op_sel_hi:[1,0] neg_lo:[1,0] neg_hi:[1,0]
	s_nop 0
	v_cndmask_b32_e64 v16, 0, 32, s[4:5]
	v_ldexp_f32 v9, v9, v16
	v_log_f32_e32 v9, v9
	v_pk_mul_f32 v[42:43], v[40:41], v[20:21]
	v_mul_f32_e32 v16, 0x3f317217, v9
	v_fma_f32 v16, v9, s92, -v16
	v_fmac_f32_e32 v16, 0x3377d1cf, v9
	v_fmac_f32_e32 v16, 0x3f317217, v9
	v_cmp_lt_f32_e64 s[6:7], |v9|, s90
	s_nop 1
	v_cndmask_b32_e64 v9, v9, v16, s[6:7]
	v_cndmask_b32_e64 v16, 0, v238, s[4:5]
	v_sub_f32_e32 v16, v9, v16
	v_fma_f32 v9, v41, v19, v7
	v_cmp_gt_f32_e64 s[4:5], s33, v9
	s_nop 1
	v_cndmask_b32_e64 v17, 0, 32, s[4:5]
	v_ldexp_f32 v9, v9, v17
	v_log_f32_e32 v9, v9
	s_nop 0
	v_mul_f32_e32 v17, 0x3f317217, v9
	v_fma_f32 v17, v9, s92, -v17
	v_fmac_f32_e32 v17, 0x3377d1cf, v9
; #define LAS __attribute__((address_space(3)))
; __device__ __forceinline__ float sigmoid_(float z) { return __builtin_amdgcn_rcpf(1.f + __expf(-z)); }
; template <int TYPE>
; __device__ __forceinline__ void lg_compute(const KArgs& a, unsigned char* wsb, int l, int h, int dir, const LgRaw& raw, LAS unsigned char* lds, int tid) {
;     ...
;         for (int e2 = 0; e2 < 2; ++e2) { const int i = (tid >> 4) + 32 * e2;
;             float z[8], lg[8], kk[8]; unpack8(e2 ? raw.a1 : raw.a0, z);
; #pragma unroll
;             for (int e = 0; e < 8; ++e) { const float sg = sigmoid_(fmaxf(z[e], -80.f)); lg[e] = __logf(lb[e] + (1.f - lb[e]) * sg); kk[e] = (1.f - lb[e]) * (1.f - sg); }
;             *(LAS f32x4*)(G + i * C::LDG + d8 * 8) = (f32x4){lg[0], lg[1], lg[2], lg[3]}; *(LAS f32x4*)(G + i * C::LDG + d8 * 8 + 4) = (f32x4){lg[4], lg[5], lg[6], lg[7]};
;             *(LAS bf16x8*)(Kb + i * C::LDK_ + d8 * 8) = pack8(kk); }
	v_fmac_f32_e32 v17, 0x3f317217, v9
	v_cmp_lt_f32_e64 s[6:7], |v9|, s90
	s_nop 1
	v_cndmask_b32_e64 v9, v9, v17, s[6:7]
	v_cndmask_b32_e64 v17, 0, v238, s[4:5]
	v_sub_f32_e32 v17, v9, v17
	v_max_f32_e32 v9, v23, v23
	v_max_f32_e32 v9, 0xc2a00000, v9
	v_mul_f32_e32 v9, 0xbfb8aa3b, v9
	v_exp_f32_e32 v9, v9
	s_nop 0
	v_add_f32_e32 v9, 1.0, v9
	v_rcp_f32_e32 v20, v9
	v_max_f32_e32 v9, v24, v24
	v_max_f32_e32 v9, 0xc2a00000, v9
	v_mul_f32_e32 v9, 0xbfb8aa3b, v9
	v_exp_f32_e32 v9, v9
	s_nop 0
	v_add_f32_e32 v9, 1.0, v9
	v_rcp_f32_e32 v21, v9
	v_fma_f32 v9, v44, v20, v0
	v_cmp_gt_f32_e64 s[4:5], s33, v9
	v_pk_add_f32 v[24:25], v[20:21], 1.0 op_sel_hi:[1,0] neg_lo:[1,0] neg_hi:[1,0]
	s_nop 0
	v_cndmask_b32_e64 v18, 0, 32, s[4:5]
	v_ldexp_f32 v9, v9, v18
	v_log_f32_e32 v9, v9
	v_pk_mul_f32 v[46:47], v[44:45], v[24:25]
	v_mul_f32_e32 v18, 0x3f317217, v9
	v_fma_f32 v18, v9, s92, -v18
	v_fmac_f32_e32 v18, 0x3377d1cf, v9
	v_fmac_f32_e32 v18, 0x3f317217, v9
	v_cmp_lt_f32_e64 s[6:7], |v9|, s90
	s_nop 1
	v_cndmask_b32_e64 v9, v9, v18, s[6:7]
	v_cndmask_b32_e64 v18, 0, v238, s[4:5]
	v_sub_f32_e32 v18, v9, v18
	v_fma_f32 v9, v45, v21, v1
	v_cmp_gt_f32_e64 s[4:5], s33, v9
	s_nop 1
	v_cndmask_b32_e64 v19, 0, 32, s[4:5]
	v_ldexp_f32 v9, v9, v19
	v_log_f32_e32 v9, v9
	s_nop 0
	v_mul_f32_e32 v19, 0x3f317217, v9
	v_fma_f32 v19, v9, s92, -v19
	v_fmac_f32_e32 v19, 0x3377d1cf, v9
	v_fmac_f32_e32 v19, 0x3f317217, v9
	v_cmp_lt_f32_e64 s[6:7], |v9|, s90
	s_nop 1
	v_cndmask_b32_e64 v9, v9, v19, s[6:7]
	v_cndmask_b32_e64 v19, 0, v238, s[4:5]
	v_sub_f32_e32 v19, v9, v19
	v_max_f32_e32 v9, v28, v28
	v_max_f32_e32 v9, 0xc2a00000, v9
	v_mul_f32_e32 v9, 0xbfb8aa3b, v9
	v_exp_f32_e32 v9, v9
	s_nop 0
	v_add_f32_e32 v9, 1.0, v9
	v_rcp_f32_e32 v24, v9
	v_max_f32_e32 v9, v29, v29
	v_max_f32_e32 v9, 0xc2a00000, v9
	v_mul_f32_e32 v9, 0xbfb8aa3b, v9
	v_exp_f32_e32 v9, v9
	s_nop 0
	v_add_f32_e32 v9, 1.0, v9
	v_rcp_f32_e32 v25, v9
	v_fma_f32 v9, v48, v24, v2
	v_cmp_gt_f32_e64 s[4:5], s33, v9
	v_pk_add_f32 v[28:29], v[24:25], 1.0 op_sel_hi:[1,0] neg_lo:[1,0] neg_hi:[1,0]
	s_nop 0
	v_cndmask_b32_e64 v20, 0, 32, s[4:5]
	v_ldexp_f32 v9, v9, v20
	v_log_f32_e32 v9, v9
	v_pk_mul_f32 v[50:51], v[48:49], v[28:29]
	v_mul_f32_e32 v20, 0x3f317217, v9
	v_fma_f32 v20, v9, s92, -v20
	v_fmac_f32_e32 v20, 0x3377d1cf, v9
	v_fmac_f32_e32 v20, 0x3f317217, v9
	v_cmp_lt_f32_e64 s[6:7], |v9|, s90
	s_nop 1
	v_cndmask_b32_e64 v9, v9, v20, s[6:7]
	v_cndmask_b32_e64 v20, 0, v238, s[4:5]
	v_sub_f32_e32 v20, v9, v20
	v_fma_f32 v9, v49, v25, v3
	v_cmp_gt_f32_e64 s[4:5], s33, v9
	s_nop 1
	v_cndmask_b32_e64 v21, 0, 32, s[4:5]
	v_ldexp_f32 v9, v9, v21
	v_log_f32_e32 v9, v9
	s_nop 0
	v_mul_f32_e32 v21, 0x3f317217, v9
	v_fma_f32 v21, v9, s92, -v21
	v_fmac_f32_e32 v21, 0x3377d1cf, v9
	v_fmac_f32_e32 v21, 0x3f317217, v9
	v_cmp_lt_f32_e64 s[6:7], |v9|, s90
	s_nop 1
	v_cndmask_b32_e64 v9, v9, v21, s[6:7]
	v_cndmask_b32_e64 v21, 0, v238, s[4:5]
	v_mad_u64_u32 v[52:53], s[4:5], v8, s91, v[22:23]
	s_mov_b32 s4, 0x54000
	s_nop 0
	v_add_co_u32_e64 v10, s[4:5], s4, v10
	v_sub_f32_e32 v21, v9, v21
	s_nop 0
	v_addc_co_u32_e64 v11, s[4:5], 0, v11, s[4:5]
	global_load_dwordx4 v[22:25], v[10:11], off
	s_nop 0
	global_load_dwordx4 v[26:29], v[26:27], off
	s_nop 0
	global_load_dwordx4 v[30:33], v[30:31], off
	ds_write_b128 v52, v[14:17]
	ds_write_b128 v52, v[18:21] offset:16
	v_cvt_pk_bf16_f32 v14, v38, v39
	v_cvt_pk_bf16_f32 v15, v42, v43
	v_cvt_pk_bf16_f32 v16, v46, v47
	v_cvt_pk_bf16_f32 v17, v50, v51
	v_mad_u64_u32 v[10:11], s[4:5], v8, s93, v[34:35]
	ds_write_b128 v10, v[14:17] offset:33792
	s_waitcnt vmcnt(0) lgkmcnt(0)
	v_lshlrev_b32_e32 v9, 16, v22
	v_max_f32_e32 v9, v9, v9
	v_max_f32_e32 v9, 0xc2a00000, v9
	v_mul_f32_e32 v9, 0xbfb8aa3b, v9
	v_exp_f32_e32 v9, v9
	v_and_b32_e32 v11, 0xffff0000, v22
	v_lshlrev_b32_e32 v16, 16, v23
	v_and_b32_e32 v17, 0xffff0000, v23
	v_add_f32_e32 v9, 1.0, v9
	v_rcp_f32_e32 v14, v9
	v_lshlrev_b32_e32 v18, 16, v24
	v_and_b32_e32 v19, 0xffff0000, v24
	v_lshlrev_b32_e32 v20, 16, v25
	v_fma_f32 v4, v36, v14, v4
	v_cmp_gt_f32_e64 s[4:5], s33, v4
	v_and_b32_e32 v21, 0xffff0000, v25
	s_nop 0
	v_cndmask_b32_e64 v9, 0, 32, s[4:5]
	v_ldexp_f32 v4, v4, v9
	v_log_f32_e32 v4, v4
	s_nop 0
	v_mul_f32_e32 v9, 0x3f317217, v4
	v_fma_f32 v9, v4, s92, -v9
	v_fmac_f32_e32 v9, 0x3377d1cf, v4
	v_fmac_f32_e32 v9, 0x3f317217, v4
	v_cmp_lt_f32_e64 s[6:7], |v4|, s90
	s_nop 1
	v_cndmask_b32_e64 v4, v4, v9, s[6:7]
	v_cndmask_b32_e64 v9, 0, v238, s[4:5]
	v_sub_f32_e32 v4, v4, v9
	v_max_f32_e32 v9, v11, v11
	v_max_f32_e32 v9, 0xc2a00000, v9
	v_mul_f32_e32 v9, 0xbfb8aa3b, v9
	v_exp_f32_e32 v9, v9
	s_nop 0
	v_add_f32_e32 v9, 1.0, v9
	v_rcp_f32_e32 v15, v9
	s_nop 0
	v_fma_f32 v5, v37, v15, v5
	v_cmp_gt_f32_e64 s[4:5], s33, v5
	v_pk_add_f32 v[14:15], v[14:15], 1.0 op_sel_hi:[1,0] neg_lo:[1,0] neg_hi:[1,0]
	s_nop 0
	v_cndmask_b32_e64 v9, 0, 32, s[4:5]
	v_ldexp_f32 v5, v5, v9
	v_log_f32_e32 v5, v5
	v_pk_mul_f32 v[14:15], v[36:37], v[14:15]
	v_mul_f32_e32 v9, 0x3f317217, v5
	v_fma_f32 v9, v5, s92, -v9
	v_fmac_f32_e32 v9, 0x3377d1cf, v5
	v_fmac_f32_e32 v9, 0x3f317217, v5
	v_cmp_lt_f32_e64 s[6:7], |v5|, s90
	s_nop 1
	v_cndmask_b32_e64 v5, v5, v9, s[6:7]
	v_cndmask_b32_e64 v9, 0, v238, s[4:5]
	v_sub_f32_e32 v5, v5, v9
	v_max_f32_e32 v9, v16, v16
	v_max_f32_e32 v9, 0xc2a00000, v9
	v_mul_f32_e32 v9, 0xbfb8aa3b, v9
	v_exp_f32_e32 v9, v9
	s_nop 0
	v_add_f32_e32 v9, 1.0, v9
	v_rcp_f32_e32 v16, v9
	s_nop 0
	v_fma_f32 v6, v40, v16, v6
	v_cmp_gt_f32_e64 s[4:5], s33, v6
	s_nop 1
	v_cndmask_b32_e64 v9, 0, 32, s[4:5]
	v_ldexp_f32 v6, v6, v9
	v_log_f32_e32 v6, v6
	s_nop 0
	v_mul_f32_e32 v9, 0x3f317217, v6
	v_fma_f32 v9, v6, s92, -v9
; #define LAS __attribute__((address_space(3)))
; __device__ __forceinline__ float sigmoid_(float z) { return __builtin_amdgcn_rcpf(1.f + __expf(-z)); }
; template <int TYPE>
; __device__ __forceinline__ void lg_compute(const KArgs& a, unsigned char* wsb, int l, int h, int dir, const LgRaw& raw, LAS unsigned char* lds, int tid) {
;     ...
;         for (int e2 = 0; e2 < 2; ++e2) { const int i = (tid >> 4) + 32 * e2;
;             float z[8], lg[8], kk[8]; unpack8(e2 ? raw.a1 : raw.a0, z);
; #pragma unroll
;             for (int e = 0; e < 8; ++e) { const float sg = sigmoid_(fmaxf(z[e], -80.f)); lg[e] = __logf(lb[e] + (1.f - lb[e]) * sg); kk[e] = (1.f - lb[e]) * (1.f - sg); }
;             *(LAS f32x4*)(G + i * C::LDG + d8 * 8) = (f32x4){lg[0], lg[1], lg[2], lg[3]}; *(LAS f32x4*)(G + i * C::LDG + d8 * 8 + 4) = (f32x4){lg[4], lg[5], lg[6], lg[7]};
;             *(LAS bf16x8*)(Kb + i * C::LDK_ + d8 * 8) = pack8(kk); }
; __device__ __forceinline__ void vT_write(const VRaw& r, LAS unsigned char* lds, int tid) {
;     LAS bf16_t* VT = (LAS bf16_t*)(lds + SC_VT);
;     const int v8 = tid & 15;
; #pragma unroll
;     for (int e2 = 0; e2 < 2; ++e2) { const int i = (tid >> 4) + 32 * e2; const bf16x8 x = e2 ? r.x1 : r.x0; const int pc = ((((i >> 3) ^ (v8 & 7)) << 3) | (i & 7));
; #pragma unroll
;         for (int e = 0; e < 8; ++e) VT[(v8 * 8 + e) * LDT + pc] = (bf16_t)x[e]; }
; }
	v_fmac_f32_e32 v9, 0x3377d1cf, v6
	v_fmac_f32_e32 v9, 0x3f317217, v6
	v_cmp_lt_f32_e64 s[6:7], |v6|, s90
	s_nop 1
	v_cndmask_b32_e64 v6, v6, v9, s[6:7]
	v_cndmask_b32_e64 v9, 0, v238, s[4:5]
	v_sub_f32_e32 v6, v6, v9
	v_max_f32_e32 v9, v17, v17
	v_max_f32_e32 v9, 0xc2a00000, v9
	v_mul_f32_e32 v9, 0xbfb8aa3b, v9
	v_exp_f32_e32 v9, v9
	s_nop 0
	v_add_f32_e32 v9, 1.0, v9
	v_rcp_f32_e32 v17, v9
	s_nop 0
	v_fmac_f32_e32 v7, v41, v17
	v_cmp_gt_f32_e64 s[4:5], s33, v7
	v_pk_add_f32 v[16:17], v[16:17], 1.0 op_sel_hi:[1,0] neg_lo:[1,0] neg_hi:[1,0]
	s_nop 0
	v_cndmask_b32_e64 v9, 0, 32, s[4:5]
	v_ldexp_f32 v7, v7, v9
	v_log_f32_e32 v7, v7
	v_pk_mul_f32 v[16:17], v[40:41], v[16:17]
	v_mul_f32_e32 v9, 0x3f317217, v7
	v_fma_f32 v9, v7, s92, -v9
	v_fmac_f32_e32 v9, 0x3377d1cf, v7
	v_fmac_f32_e32 v9, 0x3f317217, v7
	v_cmp_lt_f32_e64 s[6:7], |v7|, s90
	s_nop 1
	v_cndmask_b32_e64 v7, v7, v9, s[6:7]
	v_cndmask_b32_e64 v9, 0, v238, s[4:5]
	v_sub_f32_e32 v7, v7, v9
	v_max_f32_e32 v9, v18, v18
	v_max_f32_e32 v9, 0xc2a00000, v9
	v_mul_f32_e32 v9, 0xbfb8aa3b, v9
	v_exp_f32_e32 v9, v9
	s_nop 0
	v_add_f32_e32 v9, 1.0, v9
	v_rcp_f32_e32 v18, v9
	s_nop 0
	v_fma_f32 v0, v44, v18, v0
	v_cmp_gt_f32_e64 s[4:5], s33, v0
	s_nop 1
	v_cndmask_b32_e64 v9, 0, 32, s[4:5]
	v_ldexp_f32 v0, v0, v9
	v_log_f32_e32 v0, v0
	s_nop 0
	v_mul_f32_e32 v9, 0x3f317217, v0
	v_fma_f32 v9, v0, s92, -v9
	v_fmac_f32_e32 v9, 0x3377d1cf, v0
	v_fmac_f32_e32 v9, 0x3f317217, v0
	v_cmp_lt_f32_e64 s[6:7], |v0|, s90
	s_nop 1
	v_cndmask_b32_e64 v0, v0, v9, s[6:7]
	v_cndmask_b32_e64 v9, 0, v238, s[4:5]
	v_sub_f32_e32 v0, v0, v9
	v_max_f32_e32 v9, v19, v19
	v_max_f32_e32 v9, 0xc2a00000, v9
	v_mul_f32_e32 v9, 0xbfb8aa3b, v9
	v_exp_f32_e32 v9, v9
	s_nop 0
	v_add_f32_e32 v9, 1.0, v9
	v_rcp_f32_e32 v19, v9
	s_nop 0
	v_fma_f32 v1, v45, v19, v1
	v_cmp_gt_f32_e64 s[4:5], s33, v1
	v_pk_add_f32 v[18:19], v[18:19], 1.0 op_sel_hi:[1,0] neg_lo:[1,0] neg_hi:[1,0]
	s_nop 0
	v_cndmask_b32_e64 v9, 0, 32, s[4:5]
	v_ldexp_f32 v1, v1, v9
	v_log_f32_e32 v1, v1
	v_pk_mul_f32 v[18:19], v[44:45], v[18:19]
	v_mul_f32_e32 v9, 0x3f317217, v1
	v_fma_f32 v9, v1, s92, -v9
	v_fmac_f32_e32 v9, 0x3377d1cf, v1
	v_fmac_f32_e32 v9, 0x3f317217, v1
	v_cmp_lt_f32_e64 s[6:7], |v1|, s90
	s_nop 1
	v_cndmask_b32_e64 v1, v1, v9, s[6:7]
	v_cndmask_b32_e64 v9, 0, v238, s[4:5]
	v_sub_f32_e32 v1, v1, v9
	v_max_f32_e32 v9, v20, v20
	v_max_f32_e32 v9, 0xc2a00000, v9
	v_mul_f32_e32 v9, 0xbfb8aa3b, v9
	v_exp_f32_e32 v9, v9
	s_nop 0
	v_add_f32_e32 v9, 1.0, v9
	v_rcp_f32_e32 v20, v9
	s_nop 0
	v_fma_f32 v2, v48, v20, v2
	v_cmp_gt_f32_e64 s[4:5], s33, v2
	s_nop 1
	v_cndmask_b32_e64 v9, 0, 32, s[4:5]
	v_ldexp_f32 v2, v2, v9
	v_log_f32_e32 v2, v2
	s_nop 0
	v_mul_f32_e32 v9, 0x3f317217, v2
	v_fma_f32 v9, v2, s92, -v9
	v_fmac_f32_e32 v9, 0x3377d1cf, v2
	v_fmac_f32_e32 v9, 0x3f317217, v2
	v_cmp_lt_f32_e64 s[6:7], |v2|, s90
	s_nop 1
	v_cndmask_b32_e64 v2, v2, v9, s[6:7]
	v_cndmask_b32_e64 v9, 0, v238, s[4:5]
	v_sub_f32_e32 v2, v2, v9
	v_max_f32_e32 v9, v21, v21
	v_max_f32_e32 v9, 0xc2a00000, v9
	v_mul_f32_e32 v9, 0xbfb8aa3b, v9
	v_exp_f32_e32 v9, v9
	s_nop 0
	v_add_f32_e32 v9, 1.0, v9
	v_rcp_f32_e32 v21, v9
	s_nop 0
	v_fmac_f32_e32 v3, v49, v21
	v_cmp_gt_f32_e64 s[4:5], s33, v3
	v_pk_add_f32 v[20:21], v[20:21], 1.0 op_sel_hi:[1,0] neg_lo:[1,0] neg_hi:[1,0]
	s_nop 0
	v_cndmask_b32_e64 v9, 0, 32, s[4:5]
	v_ldexp_f32 v3, v3, v9
	v_log_f32_e32 v3, v3
	v_pk_mul_f32 v[20:21], v[48:49], v[20:21]
	v_mul_f32_e32 v9, 0x3f317217, v3
	v_fma_f32 v9, v3, s92, -v9
	v_fmac_f32_e32 v9, 0x3377d1cf, v3
	v_fmac_f32_e32 v9, 0x3f317217, v3
	v_cmp_lt_f32_e64 s[6:7], |v3|, s90
	s_nop 1
	v_cndmask_b32_e64 v3, v3, v9, s[6:7]
	v_cndmask_b32_e64 v9, 0, v238, s[4:5]
	v_sub_f32_e32 v3, v3, v9
	ds_write_b128 v52, v[4:7] offset:16896
	ds_write_b128 v52, v[0:3] offset:16912
	v_cvt_pk_bf16_f32 v0, v14, v15
	v_cvt_pk_bf16_f32 v1, v16, v17
	v_cvt_pk_bf16_f32 v2, v18, v19
	v_cvt_pk_bf16_f32 v3, v20, v21
	ds_write_b128 v10, v[0:3] offset:42496
	v_and_b32_e32 v0, 56, v13
	v_lshlrev_b32_e32 v1, 1, v8
	v_and_b32_e32 v1, 14, v1
	v_bitop3_b32 v0, v8, v0, -8 bitop3:0x6c
	v_add_u32_e32 v1, s95, v1
	v_lshlrev_b32_e32 v0, 1, v0
	v_mul_u32_u24_e32 v3, 0x90, v35
	v_and_b32_e32 v2, -8, v8
	v_add3_u32 v0, v1, v0, v3
	ds_write_b16 v0, v26
	ds_write_b16_d16_hi v0, v26 offset:144
	ds_write_b16 v0, v27 offset:288
	ds_write_b16_d16_hi v0, v27 offset:432
	ds_write_b16 v0, v28 offset:576
	ds_write_b16_d16_hi v0, v28 offset:720
	ds_write_b16 v0, v29 offset:864
	ds_write_b16_d16_hi v0, v29 offset:1008
	v_add_u32_e32 v0, 32, v2
	v_bitop3_b32 v0, v0, v13, 56 bitop3:0x78
	v_lshlrev_b32_e32 v0, 1, v0
	v_add3_u32 v0, v1, v0, v3
	ds_write_b16 v0, v30
	ds_write_b16_d16_hi v0, v30 offset:144
	ds_write_b16 v0, v31 offset:288
	ds_write_b16_d16_hi v0, v31 offset:432
	ds_write_b16 v0, v32 offset:576
	ds_write_b16_d16_hi v0, v32 offset:720
	ds_write_b16 v0, v33 offset:864
	ds_write_b16_d16_hi v0, v33 offset:1008
	v_ashrrev_i32_e32 v0, 31, v12
	v_lshrrev_b32_e32 v0, 25, v0
	v_add_u32_e32 v0, v12, v0
	v_ashrrev_i32_e32 v1, 7, v0
	v_and_b32_e32 v0, 0x3fffff80, v0
	v_sub_u32_e32 v0, v12, v0
	v_lshlrev_b32_e32 v4, 4, v1
	v_lshlrev_b32_e32 v5, 2, v0
	v_add_u32_e32 v0, 0, v5
	v_and_or_b32 v2, s24, 15, v4
	v_mad_u64_u32 v[2:3], s[4:5], v2, s91, v[0:1]
	s_waitcnt lgkmcnt(0)
	s_barrier
; #define LAS __attribute__((address_space(3)))
; template <int TYPE>
; __device__ __forceinline__ void cumsum_g(int dir, LAS unsigned char* lds, int tid) {
;     using C = Cfg<TYPE>; constexpr int NSEG = 512 / C::DK, SEGL = 64 / NSEG;
;     LAS float* G = (LAS float*)(lds + SC_G); LAS float* SG = (LAS float*)(lds + SC_SEG);
;     const int d = tid % C::DK, seg = tid / C::DK;
;     __syncthreads();
;     float run = 0.f;
; #pragma unroll
;     for (int ii = 0; ii < SEGL; ++ii) { const int i = seg * SEGL + (dir ? SEGL - 1 - ii : ii); run += G[i * C::LDG + d]; G[i * C::LDG + d] = run; }
;     SG[seg * 128 + d] = run;
;     __syncthreads();
	ds_read_b32 v96, v2
	v_or_b32_e32 v64, s30, v4
	v_mad_u64_u32 v[64:65], s[4:5], v64, s91, v[0:1]
	ds_read_b32 v97, v64
	v_or_b32_e32 v66, s29, v4
	v_mad_u64_u32 v[66:67], s[4:5], v66, s91, v[0:1]
	ds_read_b32 v98, v66
	v_or_b32_e32 v68, s28, v4
	v_mad_u64_u32 v[68:69], s[4:5], v68, s91, v[0:1]
	ds_read_b32 v99, v68
	v_or_b32_e32 v70, s27, v4
	v_mad_u64_u32 v[70:71], s[4:5], v70, s91, v[0:1]
	ds_read_b32 v100, v70
	v_or_b32_e32 v72, s26, v4
	v_mad_u64_u32 v[72:73], s[4:5], v72, s91, v[0:1]
	ds_read_b32 v101, v72
	v_or_b32_e32 v74, s25, v4
	v_mad_u64_u32 v[74:75], s[4:5], v74, s91, v[0:1]
	ds_read_b32 v102, v74
	s_add_i32 s4, s16, 7
	v_or_b32_e32 v76, s4, v4
	v_mad_u64_u32 v[76:77], s[4:5], v76, s91, v[0:1]
	ds_read_b32 v103, v76
	v_subrev_u32_e32 v78, s16, v4
	v_mad_u64_u32 v[78:79], s[4:5], v78, s91, v[0:1]
	ds_read_b32 v104, v78 offset:4224
	v_or_b32_e32 v80, s23, v4
	v_mad_u64_u32 v[80:81], s[4:5], v80, s91, v[0:1]
	ds_read_b32 v105, v80
	v_or_b32_e32 v82, s22, v4
	v_mad_u64_u32 v[82:83], s[4:5], v82, s91, v[0:1]
	ds_read_b32 v106, v82
	v_or_b32_e32 v84, s21, v4
	v_mad_u64_u32 v[84:85], s[4:5], v84, s91, v[0:1]
	ds_read_b32 v107, v84
	v_or_b32_e32 v86, s20, v4
	v_mad_u64_u32 v[86:87], s[4:5], v86, s91, v[0:1]
	ds_read_b32 v108, v86
	v_or_b32_e32 v88, s19, v4
	v_mad_u64_u32 v[88:89], s[4:5], v88, s91, v[0:1]
	ds_read_b32 v109, v88
	v_or_b32_e32 v90, s18, v4
	v_mad_u64_u32 v[90:91], s[4:5], v90, s91, v[0:1]
	ds_read_b32 v110, v90
	v_or_b32_e32 v92, s17, v4
	v_mad_u64_u32 v[92:93], s[4:5], v92, s91, v[0:1]
	ds_read_b32 v111, v92
	v_cmp_gt_i32_e64 s[4:5], s0, v12
	s_movk_i32 s0, 0x7f
	v_cmp_lt_i32_e64 s[6:7], s0, v12
	v_cndmask_b32_e64 v4, 0, 1, s[4:5]
	s_waitcnt lgkmcnt(0)
	v_add_f32_e32 v6, 0, v96
	ds_write_b32 v2, v6
	v_add_f32_e32 v6, v6, v97
	ds_write_b32 v64, v6
	v_add_f32_e32 v6, v6, v98
	ds_write_b32 v66, v6
	v_add_f32_e32 v6, v6, v99
	ds_write_b32 v68, v6
	v_add_f32_e32 v6, v6, v100
	ds_write_b32 v70, v6
	v_add_f32_e32 v6, v6, v101
	ds_write_b32 v72, v6
	v_add_f32_e32 v6, v6, v102
	ds_write_b32 v74, v6
	v_add_f32_e32 v6, v6, v103
	ds_write_b32 v76, v6
	v_add_f32_e32 v6, v6, v104
	ds_write_b32 v78, v6 offset:4224
	v_add_f32_e32 v6, v6, v105
	ds_write_b32 v80, v6
	v_add_f32_e32 v6, v6, v106
	ds_write_b32 v82, v6
	v_add_f32_e32 v6, v6, v107
	ds_write_b32 v84, v6
	v_add_f32_e32 v6, v6, v108
	ds_write_b32 v86, v6
	v_add_f32_e32 v6, v6, v109
	ds_write_b32 v88, v6
	v_add_f32_e32 v6, v6, v110
	ds_write_b32 v90, v6
	v_add_f32_e32 v3, v6, v111
	ds_write_b32 v92, v3


; template <int TYPE>
; __device__ __forceinline__ void cumsum_g(int dir, LAS unsigned char* lds, int tid) {
;     ...
;     for (int ii = 0; ii < SEGL; ++ii) { const int i = seg * SEGL + (dir ? SEGL - 1 - ii : ii); run += G[i * C::LDG + d]; G[i * C::LDG + d] = run; }
;     SG[seg * 128 + d] = run;
;     __syncthreads();
;     float off = 0.f;
; #pragma unroll
;     for (int s = 0; s < NSEG; ++s) { const bool before = dir ? (s > seg) : (s < seg); if (before) off += SG[s * 128 + d]; }
	v_lshl_add_u32 v2, v12, 2, s74
	ds_write_b32 v2, v3
	v_cndmask_b32_e64 v3, 0, 1, s[6:7]
	v_cndmask_b32_e32 v3, v4, v3, vcc
	v_and_b32_e32 v3, 1, v3
	v_add_u32_e32 v2, s74, v5
	v_cmp_eq_u32_e64 s[4:5], 1, v3
	v_mov_b32_e32 v3, 0
	s_waitcnt lgkmcnt(0)
	s_barrier
	s_and_saveexec_b64 s[6:7], s[4:5]
	s_cbranch_execz .LBB0_267
	ds_read_b32 v3, v2
	s_waitcnt lgkmcnt(0)
	v_add_f32_e32 v3, 0, v3

; template <int TYPE>
; __device__ __forceinline__ LgRaw lg_issue(const bf16_t* u, int h, int dir, size_t tok0, int tid) {
;     LgRaw r;
;     if constexpr (TYPE == 1) {
;         const int i0 = tid >> 4, d8 = tid & 15, col = (dir ? C_HFB : C_HFF) + h * 128 + d8 * 8;
;         r.a0 = *(const bf16x8*)(u + (tok0 + i0) * DINP + col); r.a1 = *(const bf16x8*)(u + (tok0 + 32 + i0) * DINP + col); r.k = r.a0;
;     } else {
;         const int i = tid >> 3, d8 = tid & 7; const bf16_t* ur = u + (tok0 + i) * DINP;
;         r.a0 = *(const bf16x8*)(ur + (dir ? C_GAB : C_GAF)); r.a1 = *(const bf16x8*)(ur + (dir ? C_GAB : C_GAF) + 8); r.k = *(const bf16x8*)(ur + C_GK + h * 64 + d8 * 8);
;     }
;     return r;
; template <int TYPE>
; __device__ __forceinline__ void lg_compute(const KArgs& a, unsigned char* wsb, int l, int h, int dir, const LgRaw& raw, LAS unsigned char* lds, int tid) {
;     ...
;     } else {
;         const int i = tid >> 3, d8 = tid & 7;
;         float ua[16]; unpack8(raw.a0, ua); unpack8(raw.a1, ua + 8);
;         const float* up = (const float*)a.in[3] + (size_t)((l * 2 + dir) * 16) * 256 + h * 64 + d8 * 8;
;         const float* bs = (const float*)a.in[4] + (l * 2 + dir) * 256 + h * 64 + d8 * 8;
;         f32x4 z0 = *(const f32x4*)bs, z1 = *(const f32x4*)(bs + 4);
; #pragma unroll
;         for (int r = 0; r < 16; ++r) { z0 += ua[r] * *(const f32x4*)(up + r * 256); z1 += ua[r] * *(const f32x4*)(up + r * 256 + 4); }
.LBB0_288:
	s_ashr_i32 s4, s16, 11
	s_ashr_i32 s5, s4, 31
	s_lshl_b64 s[4:5], s[4:5], 14
	s_and_b32 s6, s15, 0x3fc0
	s_mov_b64 s[12:13], s[68:69]
	v_mov_b32_e32 v12, v195
	s_bfe_i32 s18, s16, 0x10008
	s_bfe_u32 s17, s16, 0x10008
	s_bfe_u32 s19, s16, 0x20009
	s_or_b32 s4, s4, s6
	s_add_u32 s6, s12, 0xe300000
	v_ashrrev_i32_e32 v8, 3, v12
	s_addc_u32 s7, s13, 0
	v_ashrrev_i32_e32 v9, 31, v8
	v_lshl_add_u64 v[0:1], s[4:5], 0, v[8:9]
	v_mov_b64_e32 v[2:3], s[6:7]
	v_mad_u64_u32 v[2:3], s[20:21], v0, s2, v[2:3]
	s_mulk_i32 s5, 0x2a00
	s_mul_hi_u32 s21, s4, 0x2a00
	s_lshl_b32 s20, s19, 7
	s_add_i32 s21, s21, s5
	s_mulk_i32 s4, 0x2a00
	s_add_u32 s4, s6, s4
	s_addc_u32 s5, s7, s21
	s_lshl_b32 s19, s19, 8
	s_add_u32 s4, s4, s19
	s_addc_u32 s5, s5, 0
	s_or_b32 s21, s17, s14
	s_lshl_b32 s72, s21, 12
	v_readlane_b32 s36, v253, 48
	s_lshl_b64 s[6:7], s[72:73], 2
	v_readlane_b32 s42, v253, 54
	v_readlane_b32 s43, v253, 55
	s_add_u32 s6, s42, s6
	s_addc_u32 s7, s43, s7
	s_add_u32 s6, s6, s19
	s_addc_u32 s7, s7, 0
	s_lshl_b32 s72, s21, 8
	v_readlane_b32 s44, v253, 56
	s_lshl_b64 s[22:23], s[72:73], 2
	v_readlane_b32 s45, v253, 57
	s_add_u32 s21, s44, s22
	s_addc_u32 s23, s45, s23
	s_add_u32 s22, s21, s19
	s_addc_u32 s23, s23, 0
	s_add_i32 s19, s17, 3
	s_cmp_eq_u32 s17, 0
	s_cselect_b64 vcc, -1, 0
	s_and_b64 s[24:25], vcc, exec
	s_movk_i32 s21, 0x820
	v_lshlrev_b32_e32 v9, 3, v12
	v_mad_i32_i24 v3, v1, s2, v3
	s_cselect_b32 s72, 0x800, s21
	s_mov_b32 s21, s73
	v_and_b32_e32 v13, 56, v9
	v_ashrrev_i32_e32 v35, 4, v12
	s_movk_i32 s2, 0x2a00
	v_lshl_add_u64 v[0:1], v[2:3], 0, s[20:21]
	v_lshlrev_b32_e32 v112, 1, v13
	v_mov_b64_e32 v[6:7], s[4:5]
	v_and_b32_e32 v37, 0x78, v9
	v_add_u32_e32 v16, 32, v35
	v_lshl_add_u64 v[10:11], v[2:3], 0, s[72:73]
	v_lshl_add_u64 v[0:1], v[0:1], 0, v[112:113]
	v_mad_i64_i32 v[4:5], s[4:5], v35, s2, v[6:7]
	v_lshlrev_b32_e32 v14, 1, v37
	v_mov_b32_e32 v15, v113
	v_mad_i64_i32 v[6:7], s[4:5], v16, s2, v[6:7]
	s_waitcnt lgkmcnt(0)
	s_barrier
	global_load_dwordx4 v[0:3], v[0:1], off offset:512
	v_lshl_add_u64 v[4:5], v[4:5], 0, v[14:15]
	v_lshl_add_u64 v[6:7], v[6:7], 0, v[14:15]
	global_load_dwordx4 v[14:17], v[10:11], off
	global_load_dwordx4 v[64:67], v[10:11], off offset:16
	v_lshlrev_b32_e32 v68, 2, v13
	v_add_u32_e32 v69, 0x1000, v68
	v_add_u32_e32 v94, 0x2000, v68
	v_add_u32_e32 v95, 0x3000, v68
	s_mov_b64 s[4:5], 0x1000
	s_movk_i32 s0, 0x3000
	s_mov_b32 s20, 0xbfb8aa3b
	s_movk_i32 s93, 0x110
	v_readlane_b32 s37, v253, 49
	v_readlane_b32 s38, v253, 50
	v_readlane_b32 s39, v253, 51
	v_readlane_b32 s40, v253, 52
	v_readlane_b32 s41, v253, 53
	v_readlane_b32 s46, v253, 58
	v_readlane_b32 s47, v253, 59
	v_readlane_b32 s48, v253, 60
	v_readlane_b32 s49, v253, 61
	v_readlane_b32 s50, v253, 62
	v_readlane_b32 s51, v253, 63
	global_load_dwordx4 v[70:73], v68, s[22:23] offset:16
	global_load_dwordx4 v[74:77], v68, s[22:23]
	global_load_dwordx4 v[114:117], v68, s[6:7] offset:16
	global_load_dwordx4 v[118:121], v68, s[6:7]
	global_load_dwordx4 v[122:125], v68, s[6:7] offset:1040
	global_load_dwordx4 v[126:129], v68, s[6:7] offset:1024
	global_load_dwordx4 v[130:133], v68, s[6:7] offset:2064
	global_load_dwordx4 v[134:137], v68, s[6:7] offset:2048
	global_load_dwordx4 v[138:141], v68, s[6:7] offset:3088
	global_load_dwordx4 v[142:145], v68, s[6:7] offset:3072
	global_load_dwordx4 v[146:149], v69, s[6:7] offset:16
	global_load_dwordx4 v[150:153], v69, s[6:7]
	global_load_dwordx4 v[154:157], v69, s[6:7] offset:1040
	global_load_dwordx4 v[158:161], v69, s[6:7] offset:1024
	global_load_dwordx4 v[162:165], v69, s[6:7] offset:2064
	global_load_dwordx4 v[166:169], v69, s[6:7] offset:2048
	global_load_dwordx4 v[170:173], v69, s[6:7] offset:3088
	global_load_dwordx4 v[174:177], v69, s[6:7] offset:3072
	global_load_dwordx4 v[178:181], v94, s[6:7] offset:16
	global_load_dwordx4 v[182:185], v94, s[6:7]
	global_load_dwordx4 v[186:189], v94, s[6:7] offset:1040
	global_load_dwordx4 v[190:193], v94, s[6:7] offset:1024
	global_load_dwordx4 v[202:205], v94, s[6:7] offset:2064
	global_load_dwordx4 v[206:209], v94, s[6:7] offset:2048
	global_load_dwordx4 v[210:213], v94, s[6:7] offset:3088
	global_load_dwordx4 v[214:217], v94, s[6:7] offset:3072
	global_load_dwordx4 v[218:221], v95, s[6:7] offset:16
	global_load_dwordx4 v[222:225], v95, s[6:7]
	global_load_dwordx4 v[226:229], v95, s[6:7] offset:1040
	global_load_dwordx4 v[230:233], v95, s[6:7] offset:1024
	global_load_dwordx4 v[78:81], v95, s[6:7] offset:2064
	global_load_dwordx4 v[82:85], v95, s[6:7] offset:2048
	global_load_dwordx4 v[86:89], v95, s[6:7] offset:3088
	global_load_dwordx4 v[90:93], v95, s[6:7] offset:3072
	s_waitcnt vmcnt(0) lgkmcnt(0)
; __device__ __forceinline__ float logsigmoid_(float z) { return fminf(z, 0.f) - __logf(1.f + __expf(-fabsf(z))); }
; template <int TYPE>
; __device__ __forceinline__ void lg_compute(const KArgs& a, unsigned char* wsb, int l, int h, int dir, const LgRaw& raw, LAS unsigned char* lds, int tid) {
;     ...
;         f32x4 z0 = *(const f32x4*)bs, z1 = *(const f32x4*)(bs + 4);
; #pragma unroll
;         for (int r = 0; r < 16; ++r) { z0 += ua[r] * *(const f32x4*)(up + r * 256); z1 += ua[r] * *(const f32x4*)(up + r * 256 + 4); }
;         f32x4 g0, g1;
; #pragma unroll
;         for (int e = 0; e < 4; ++e) { g0[e] = logsigmoid_(z0[e]) * (1.f / 16.f); g1[e] = logsigmoid_(z1[e]) * (1.f / 16.f); }
	v_lshlrev_b32_e32 v30, 16, v14
	v_and_b32_e32 v32, 0xffff0000, v14
	v_lshlrev_b32_e32 v34, 16, v15
	v_and_b32_e32 v36, 0xffff0000, v15
	v_lshlrev_b32_e32 v38, 16, v16
	v_and_b32_e32 v40, 0xffff0000, v16
	v_lshlrev_b32_e32 v42, 16, v17
	v_and_b32_e32 v44, 0xffff0000, v17
	v_lshlrev_b32_e32 v10, 2, v13
	v_mov_b32_e32 v11, v113
	v_lshlrev_b32_e32 v46, 16, v64
	v_and_b32_e32 v48, 0xffff0000, v64
	v_lshlrev_b32_e32 v50, 16, v65
	v_and_b32_e32 v52, 0xffff0000, v65
	v_lshlrev_b32_e32 v54, 16, v66
	v_and_b32_e32 v56, 0xffff0000, v66
	v_lshlrev_b32_e32 v58, 16, v67
	v_and_b32_e32 v60, 0xffff0000, v67
	v_pk_fma_f32 v[22:23], v[30:31], v[114:115], v[70:71] op_sel_hi:[0,1,1]
	v_pk_fma_f32 v[24:25], v[30:31], v[116:117], v[72:73] op_sel_hi:[0,1,1]
	v_pk_fma_f32 v[26:27], v[30:31], v[118:119], v[74:75] op_sel_hi:[0,1,1]
	v_pk_fma_f32 v[28:29], v[30:31], v[120:121], v[76:77] op_sel_hi:[0,1,1]
	v_pk_fma_f32 v[22:23], v[32:33], v[122:123], v[22:23] op_sel_hi:[0,1,1]
	v_pk_fma_f32 v[24:25], v[32:33], v[124:125], v[24:25] op_sel_hi:[0,1,1]
	v_pk_fma_f32 v[26:27], v[32:33], v[126:127], v[26:27] op_sel_hi:[0,1,1]
	v_pk_fma_f32 v[28:29], v[32:33], v[128:129], v[28:29] op_sel_hi:[0,1,1]
	v_pk_fma_f32 v[22:23], v[34:35], v[130:131], v[22:23] op_sel_hi:[0,1,1]
	v_pk_fma_f32 v[24:25], v[34:35], v[132:133], v[24:25] op_sel_hi:[0,1,1]
	v_pk_fma_f32 v[26:27], v[34:35], v[134:135], v[26:27] op_sel_hi:[0,1,1]
	v_pk_fma_f32 v[28:29], v[34:35], v[136:137], v[28:29] op_sel_hi:[0,1,1]
	v_pk_fma_f32 v[22:23], v[36:37], v[138:139], v[22:23] op_sel_hi:[0,1,1]
	v_pk_fma_f32 v[24:25], v[36:37], v[140:141], v[24:25] op_sel_hi:[0,1,1]
	v_pk_fma_f32 v[26:27], v[36:37], v[142:143], v[26:27] op_sel_hi:[0,1,1]
	v_pk_fma_f32 v[28:29], v[36:37], v[144:145], v[28:29] op_sel_hi:[0,1,1]
	v_pk_fma_f32 v[22:23], v[38:39], v[146:147], v[22:23] op_sel_hi:[0,1,1]
	v_pk_fma_f32 v[24:25], v[38:39], v[148:149], v[24:25] op_sel_hi:[0,1,1]
	v_pk_fma_f32 v[26:27], v[38:39], v[150:151], v[26:27] op_sel_hi:[0,1,1]
	v_pk_fma_f32 v[28:29], v[38:39], v[152:153], v[28:29] op_sel_hi:[0,1,1]
	v_pk_fma_f32 v[22:23], v[40:41], v[154:155], v[22:23] op_sel_hi:[0,1,1]
	v_pk_fma_f32 v[24:25], v[40:41], v[156:157], v[24:25] op_sel_hi:[0,1,1]
	v_pk_fma_f32 v[26:27], v[40:41], v[158:159], v[26:27] op_sel_hi:[0,1,1]
	v_pk_fma_f32 v[28:29], v[40:41], v[160:161], v[28:29] op_sel_hi:[0,1,1]
	v_pk_fma_f32 v[22:23], v[42:43], v[162:163], v[22:23] op_sel_hi:[0,1,1]
	v_pk_fma_f32 v[24:25], v[42:43], v[164:165], v[24:25] op_sel_hi:[0,1,1]
	v_pk_fma_f32 v[26:27], v[42:43], v[166:167], v[26:27] op_sel_hi:[0,1,1]
	v_pk_fma_f32 v[28:29], v[42:43], v[168:169], v[28:29] op_sel_hi:[0,1,1]
	v_pk_fma_f32 v[22:23], v[44:45], v[170:171], v[22:23] op_sel_hi:[0,1,1]
	v_pk_fma_f32 v[24:25], v[44:45], v[172:173], v[24:25] op_sel_hi:[0,1,1]
	v_pk_fma_f32 v[26:27], v[44:45], v[174:175], v[26:27] op_sel_hi:[0,1,1]
	v_pk_fma_f32 v[28:29], v[44:45], v[176:177], v[28:29] op_sel_hi:[0,1,1]
	v_pk_fma_f32 v[22:23], v[46:47], v[178:179], v[22:23] op_sel_hi:[0,1,1]
	v_pk_fma_f32 v[24:25], v[46:47], v[180:181], v[24:25] op_sel_hi:[0,1,1]
	v_pk_fma_f32 v[26:27], v[46:47], v[182:183], v[26:27] op_sel_hi:[0,1,1]
	v_pk_fma_f32 v[28:29], v[46:47], v[184:185], v[28:29] op_sel_hi:[0,1,1]
	v_pk_fma_f32 v[22:23], v[48:49], v[186:187], v[22:23] op_sel_hi:[0,1,1]
	v_pk_fma_f32 v[24:25], v[48:49], v[188:189], v[24:25] op_sel_hi:[0,1,1]
	v_pk_fma_f32 v[26:27], v[48:49], v[190:191], v[26:27] op_sel_hi:[0,1,1]
	v_pk_fma_f32 v[28:29], v[48:49], v[192:193], v[28:29] op_sel_hi:[0,1,1]
	v_pk_fma_f32 v[22:23], v[50:51], v[202:203], v[22:23] op_sel_hi:[0,1,1]
	v_pk_fma_f32 v[24:25], v[50:51], v[204:205], v[24:25] op_sel_hi:[0,1,1]
	v_pk_fma_f32 v[26:27], v[50:51], v[206:207], v[26:27] op_sel_hi:[0,1,1]
	v_pk_fma_f32 v[28:29], v[50:51], v[208:209], v[28:29] op_sel_hi:[0,1,1]
	v_pk_fma_f32 v[22:23], v[52:53], v[210:211], v[22:23] op_sel_hi:[0,1,1]
	v_pk_fma_f32 v[24:25], v[52:53], v[212:213], v[24:25] op_sel_hi:[0,1,1]
	v_pk_fma_f32 v[26:27], v[52:53], v[214:215], v[26:27] op_sel_hi:[0,1,1]
	v_pk_fma_f32 v[28:29], v[52:53], v[216:217], v[28:29] op_sel_hi:[0,1,1]
	v_pk_fma_f32 v[22:23], v[54:55], v[218:219], v[22:23] op_sel_hi:[0,1,1]
	v_pk_fma_f32 v[24:25], v[54:55], v[220:221], v[24:25] op_sel_hi:[0,1,1]
	v_pk_fma_f32 v[26:27], v[54:55], v[222:223], v[26:27] op_sel_hi:[0,1,1]
	v_pk_fma_f32 v[28:29], v[54:55], v[224:225], v[28:29] op_sel_hi:[0,1,1]
	v_pk_fma_f32 v[22:23], v[56:57], v[226:227], v[22:23] op_sel_hi:[0,1,1]
	v_pk_fma_f32 v[24:25], v[56:57], v[228:229], v[24:25] op_sel_hi:[0,1,1]
	v_pk_fma_f32 v[26:27], v[56:57], v[230:231], v[26:27] op_sel_hi:[0,1,1]
	v_pk_fma_f32 v[28:29], v[56:57], v[232:233], v[28:29] op_sel_hi:[0,1,1]
	v_pk_fma_f32 v[22:23], v[58:59], v[78:79], v[22:23] op_sel_hi:[0,1,1]
	v_pk_fma_f32 v[24:25], v[58:59], v[80:81], v[24:25] op_sel_hi:[0,1,1]
	v_pk_fma_f32 v[26:27], v[58:59], v[82:83], v[26:27] op_sel_hi:[0,1,1]
	v_pk_fma_f32 v[28:29], v[58:59], v[84:85], v[28:29] op_sel_hi:[0,1,1]
	v_pk_fma_f32 v[14:15], v[60:61], v[90:91], v[26:27] op_sel_hi:[0,1,1]
	v_pk_fma_f32 v[16:17], v[60:61], v[92:93], v[28:29] op_sel_hi:[0,1,1]
	v_pk_fma_f32 v[18:19], v[60:61], v[86:87], v[22:23] op_sel_hi:[0,1,1]
	v_pk_fma_f32 v[20:21], v[60:61], v[88:89], v[24:25] op_sel_hi:[0,1,1]
	s_mov_b32 s0, 0x3d800000
	v_mul_f32_e64 v11, |v14|, s20
	v_exp_f32_e32 v11, v11
	v_min_f32_e32 v22, 0, v14
	v_add_f32_e32 v11, 1.0, v11
	v_cmp_gt_f32_e64 s[4:5], s33, v11
	v_min_f32_e32 v24, 0, v18
	v_min_f32_e32 v23, 0, v15
	v_cndmask_b32_e64 v14, 0, 32, s[4:5]
	v_ldexp_f32 v11, v11, v14
	v_log_f32_e32 v11, v11
	v_min_f32_e32 v25, 0, v19
	v_min_f32_e32 v26, 0, v16
; #define LAS __attribute__((address_space(3)))
; __device__ __forceinline__ float logsigmoid_(float z) { return fminf(z, 0.f) - __logf(1.f + __expf(-fabsf(z))); }
; template <int TYPE>
; __device__ __forceinline__ void lg_compute(const KArgs& a, unsigned char* wsb, int l, int h, int dir, const LgRaw& raw, LAS unsigned char* lds, int tid) {
;     ...
; #pragma unroll
;         for (int e = 0; e < 4; ++e) { g0[e] = logsigmoid_(z0[e]) * (1.f / 16.f); g1[e] = logsigmoid_(z1[e]) * (1.f / 16.f); }
;         *(LAS f32x4*)(G + i * C::LDG + d8 * 8) = g0; *(LAS f32x4*)(G + i * C::LDG + d8 * 8 + 4) = g1;
;         *(LAS bf16x8*)(Kb + i * C::LDK_ + d8 * 8) = raw.k;
; __device__ __forceinline__ void vT_write(const VRaw& r, LAS unsigned char* lds, int tid) {
;     LAS bf16_t* VT = (LAS bf16_t*)(lds + SC_VT);
;     const int v8 = tid & 15;
; #pragma unroll
;     for (int e2 = 0; e2 < 2; ++e2) { const int i = (tid >> 4) + 32 * e2; const bf16x8 x = e2 ? r.x1 : r.x0; const int pc = ((((i >> 3) ^ (v8 & 7)) << 3) | (i & 7));
; #pragma unroll
;         for (int e = 0; e < 8; ++e) VT[(v8 * 8 + e) * LDT + pc] = (bf16_t)x[e]; }
; }
	v_mul_f32_e32 v14, 0x3f317217, v11
	v_fma_f32 v14, v11, s92, -v14
	v_fmac_f32_e32 v14, 0x3377d1cf, v11
	v_fmac_f32_e32 v14, 0x3f317217, v11
	v_cmp_lt_f32_e64 s[6:7], |v11|, s90
	v_min_f32_e32 v28, 0, v20
	v_min_f32_e32 v27, 0, v17
	v_cndmask_b32_e64 v11, v11, v14, s[6:7]
	v_cndmask_b32_e64 v14, 0, v238, s[4:5]
	v_sub_f32_e32 v14, v11, v14
	v_mul_f32_e64 v11, |v18|, s20
	v_exp_f32_e32 v11, v11
	v_min_f32_e32 v29, 0, v21
	v_add_f32_e32 v11, 1.0, v11
	v_cmp_gt_f32_e64 s[4:5], s33, v11
	s_nop 1
	v_cndmask_b32_e64 v18, 0, 32, s[4:5]
	v_ldexp_f32 v11, v11, v18
	v_log_f32_e32 v11, v11
	s_nop 0
	v_mul_f32_e32 v18, 0x3f317217, v11
	v_fma_f32 v18, v11, s92, -v18
	v_fmac_f32_e32 v18, 0x3377d1cf, v11
	v_fmac_f32_e32 v18, 0x3f317217, v11
	v_cmp_lt_f32_e64 s[6:7], |v11|, s90
	s_nop 1
	v_cndmask_b32_e64 v11, v11, v18, s[6:7]
	v_cndmask_b32_e64 v18, 0, v238, s[4:5]
	v_sub_f32_e32 v18, v11, v18
	v_mul_f32_e64 v11, |v15|, s20
	v_exp_f32_e32 v11, v11
	s_nop 0
	v_add_f32_e32 v11, 1.0, v11
	v_cmp_gt_f32_e64 s[4:5], s33, v11
	s_nop 1
	v_cndmask_b32_e64 v15, 0, 32, s[4:5]
	v_ldexp_f32 v11, v11, v15
	v_log_f32_e32 v11, v11
	s_nop 0
	v_mul_f32_e32 v15, 0x3f317217, v11
	v_fma_f32 v15, v11, s92, -v15
	v_fmac_f32_e32 v15, 0x3377d1cf, v11
	v_fmac_f32_e32 v15, 0x3f317217, v11
	v_cmp_lt_f32_e64 s[6:7], |v11|, s90
	s_nop 1
	v_cndmask_b32_e64 v11, v11, v15, s[6:7]
	v_cndmask_b32_e64 v15, 0, v238, s[4:5]
	v_sub_f32_e32 v15, v11, v15
	v_mul_f32_e64 v11, |v19|, s20
	v_exp_f32_e32 v11, v11
	v_pk_add_f32 v[14:15], v[22:23], v[14:15] neg_lo:[0,1] neg_hi:[0,1]
	v_add_f32_e32 v11, 1.0, v11
	v_cmp_gt_f32_e64 s[4:5], s33, v11
	v_pk_mul_f32 v[14:15], v[14:15], s[0:1] op_sel_hi:[1,0]
	s_nop 0
	v_cndmask_b32_e64 v19, 0, 32, s[4:5]
	v_ldexp_f32 v11, v11, v19
	v_log_f32_e32 v11, v11
	s_nop 0
	v_mul_f32_e32 v19, 0x3f317217, v11
	v_fma_f32 v19, v11, s92, -v19
	v_fmac_f32_e32 v19, 0x3377d1cf, v11
	v_fmac_f32_e32 v19, 0x3f317217, v11
	v_cmp_lt_f32_e64 s[6:7], |v11|, s90
	s_nop 1
	v_cndmask_b32_e64 v11, v11, v19, s[6:7]
	v_cndmask_b32_e64 v19, 0, v238, s[4:5]
	v_sub_f32_e32 v19, v11, v19
	v_mul_f32_e64 v11, |v16|, s20
	v_exp_f32_e32 v11, v11
	v_pk_add_f32 v[18:19], v[24:25], v[18:19] neg_lo:[0,1] neg_hi:[0,1]
	global_load_dwordx4 v[22:25], v[4:5], off offset:1024
	s_nop 0
	global_load_dwordx4 v[4:7], v[6:7], off offset:1024
	v_pk_mul_f32 v[18:19], v[18:19], s[0:1] op_sel_hi:[1,0]
	v_add_f32_e32 v11, 1.0, v11
	v_cmp_gt_f32_e64 s[4:5], s33, v11
	s_nop 1
	v_cndmask_b32_e64 v16, 0, 32, s[4:5]
	v_ldexp_f32 v11, v11, v16
	v_log_f32_e32 v11, v11
	s_nop 0
	v_mul_f32_e32 v16, 0x3f317217, v11
	v_fma_f32 v16, v11, s92, -v16
	v_fmac_f32_e32 v16, 0x3377d1cf, v11
	v_fmac_f32_e32 v16, 0x3f317217, v11
	v_cmp_lt_f32_e64 s[6:7], |v11|, s90
	s_nop 1
	v_cndmask_b32_e64 v11, v11, v16, s[6:7]
	v_cndmask_b32_e64 v16, 0, v238, s[4:5]
	v_sub_f32_e32 v16, v11, v16
	v_mul_f32_e64 v11, |v20|, s20
	v_exp_f32_e32 v11, v11
	s_nop 0
	v_add_f32_e32 v11, 1.0, v11
	v_cmp_gt_f32_e64 s[4:5], s33, v11
	s_nop 1
	v_cndmask_b32_e64 v20, 0, 32, s[4:5]
	v_ldexp_f32 v11, v11, v20
	v_log_f32_e32 v11, v11
	s_nop 0
	v_mul_f32_e32 v20, 0x3f317217, v11
	v_fma_f32 v20, v11, s92, -v20
	v_fmac_f32_e32 v20, 0x3377d1cf, v11
	v_fmac_f32_e32 v20, 0x3f317217, v11
	v_cmp_lt_f32_e64 s[6:7], |v11|, s90
	s_nop 1
	v_cndmask_b32_e64 v11, v11, v20, s[6:7]
	v_cndmask_b32_e64 v20, 0, v238, s[4:5]
	v_sub_f32_e32 v20, v11, v20
	v_mul_f32_e64 v11, |v17|, s20
	v_exp_f32_e32 v11, v11
	s_nop 0
	v_add_f32_e32 v11, 1.0, v11
	v_cmp_gt_f32_e64 s[4:5], s33, v11
	s_nop 1
	v_cndmask_b32_e64 v17, 0, 32, s[4:5]
	v_ldexp_f32 v11, v11, v17
	v_log_f32_e32 v11, v11
	s_nop 0
	v_mul_f32_e32 v17, 0x3f317217, v11
	v_fma_f32 v17, v11, s92, -v17
	v_fmac_f32_e32 v17, 0x3377d1cf, v11
	v_fmac_f32_e32 v17, 0x3f317217, v11
	v_cmp_lt_f32_e64 s[6:7], |v11|, s90
	s_nop 1
	v_cndmask_b32_e64 v11, v11, v17, s[6:7]
	v_cndmask_b32_e64 v17, 0, v238, s[4:5]
	v_sub_f32_e32 v17, v11, v17
	v_mul_f32_e64 v11, |v21|, s20
	v_exp_f32_e32 v11, v11
	v_pk_add_f32 v[16:17], v[26:27], v[16:17] neg_lo:[0,1] neg_hi:[0,1]
	v_add_f32_e32 v11, 1.0, v11
	v_cmp_gt_f32_e64 s[4:5], s33, v11
	v_pk_mul_f32 v[16:17], v[16:17], s[0:1] op_sel_hi:[1,0]
	s_nop 0
	v_cndmask_b32_e64 v21, 0, 32, s[4:5]
	v_ldexp_f32 v11, v11, v21
	v_log_f32_e32 v11, v11
	s_nop 0
	v_mul_f32_e32 v21, 0x3f317217, v11
	v_fma_f32 v21, v11, s92, -v21
	v_fmac_f32_e32 v21, 0x3377d1cf, v11
	v_fmac_f32_e32 v21, 0x3f317217, v11
	v_cmp_lt_f32_e64 s[6:7], |v11|, s90
	s_nop 1
	v_cndmask_b32_e64 v11, v11, v21, s[6:7]
	v_cndmask_b32_e64 v21, 0, v238, s[4:5]
	s_movk_i32 s6, 0x110
	v_sub_f32_e32 v21, v11, v21
	v_mul_lo_u32 v11, v8, s6
	v_add_u32_e32 v11, 0, v11
	v_pk_add_f32 v[20:21], v[28:29], v[20:21] neg_lo:[0,1] neg_hi:[0,1]
	v_add_u32_e32 v10, v11, v10
	v_pk_mul_f32 v[20:21], v[20:21], s[0:1] op_sel_hi:[1,0]
	ds_write_b128 v10, v[14:17]
	ds_write_b128 v10, v[18:21] offset:16
	v_lshlrev_b32_e32 v10, 7, v8
	v_sub_u32_e32 v10, v11, v10
	v_add_u32_e32 v10, v10, v112
	ds_write_b128 v10, v[0:3] offset:33792
	v_and_b32_e32 v1, -8, v35
	v_lshlrev_b32_e32 v0, 1, v35
	v_add_u32_e32 v1, 32, v1
	v_and_b32_e32 v0, 14, v0
	v_bitop3_b32 v2, v35, v13, -8 bitop3:0x6c
	v_bitop3_b32 v1, v1, v9, 56 bitop3:0x78
	v_add_u32_e32 v0, s95, v0
	v_lshlrev_b32_e32 v2, 1, v2
	v_mul_u32_u24_e32 v3, 0x90, v37
	v_lshlrev_b32_e32 v1, 1, v1
	v_add3_u32 v2, v0, v2, v3
	v_add3_u32 v0, v0, v1, v3
	s_waitcnt vmcnt(0) lgkmcnt(0)
	ds_write_b16 v2, v22
	ds_write_b16_d16_hi v2, v22 offset:144
	ds_write_b16 v2, v23 offset:288
	ds_write_b16_d16_hi v2, v23 offset:432
	ds_write_b16 v2, v24 offset:576
	ds_write_b16_d16_hi v2, v24 offset:720
	ds_write_b16 v2, v25 offset:864
	ds_write_b16_d16_hi v2, v25 offset:1008
	ds_write_b16 v0, v4
	ds_write_b16_d16_hi v0, v4 offset:144
	ds_write_b16 v0, v5 offset:288
	ds_write_b16_d16_hi v0, v5 offset:432
	ds_write_b16 v0, v6 offset:576
	ds_write_b16_d16_hi v0, v6 offset:720
	ds_write_b16 v0, v7 offset:864
	ds_write_b16_d16_hi v0, v7 offset:1008
	v_ashrrev_i32_e32 v0, 31, v12
	v_lshrrev_b32_e32 v0, 26, v0
	v_add_u32_e32 v0, v12, v0
	v_ashrrev_i32_e32 v1, 6, v0
	v_and_b32_e32 v0, 0x3fffffc0, v0
	v_sub_u32_e32 v0, v12, v0
	v_lshlrev_b32_e32 v4, 3, v1
	v_lshlrev_b32_e32 v5, 2, v0
	v_add_u32_e32 v0, 0, v5
	v_and_or_b32 v2, s18, 7, v4
	v_mad_u64_u32 v[2:3], s[4:5], v2, s6, v[0:1]
	s_waitcnt lgkmcnt(0)
	s_barrier
; #define LAS __attribute__((address_space(3)))
; template <int TYPE>
; __device__ __forceinline__ void cumsum_g(int dir, LAS unsigned char* lds, int tid) {
;     using C = Cfg<TYPE>; constexpr int NSEG = 512 / C::DK, SEGL = 64 / NSEG;
;     LAS float* G = (LAS float*)(lds + SC_G); LAS float* SG = (LAS float*)(lds + SC_SEG);
;     const int d = tid % C::DK, seg = tid / C::DK;
;     __syncthreads();
;     float run = 0.f;
; #pragma unroll
;     for (int ii = 0; ii < SEGL; ++ii) { const int i = seg * SEGL + (dir ? SEGL - 1 - ii : ii); run += G[i * C::LDG + d]; G[i * C::LDG + d] = run; }
;     SG[seg * 128 + d] = run;
;     __syncthreads();
	ds_read_b32 v80, v2
	s_cselect_b32 s4, 1, 6
	s_movk_i32 s0, 0xffc1
	v_or_b32_e32 v64, s4, v4
	v_mad_u64_u32 v[64:65], s[4:5], v64, s6, v[0:1]
	ds_read_b32 v81, v64
	s_cselect_b32 s4, 2, 5
	v_or_b32_e32 v66, s4, v4
	v_mad_u64_u32 v[66:67], s[4:5], v66, s6, v[0:1]
	ds_read_b32 v82, v66
	v_or_b32_e32 v68, s19, v4
	v_mad_u64_u32 v[68:69], s[4:5], v68, s6, v[0:1]
	ds_read_b32 v83, v68
	v_subrev_u32_e32 v70, s17, v4
	v_mad_u64_u32 v[70:71], s[4:5], v70, s6, v[0:1]
	ds_read_b32 v84, v70 offset:1088
	s_cselect_b32 s4, 5, 2
	v_or_b32_e32 v72, s4, v4
	v_mad_u64_u32 v[72:73], s[4:5], v72, s6, v[0:1]
	ds_read_b32 v85, v72
	s_cselect_b32 s4, 6, 1
	v_or_b32_e32 v74, s4, v4
	v_mad_u64_u32 v[74:75], s[4:5], v74, s6, v[0:1]
	ds_read_b32 v86, v74
	s_cselect_b32 s4, 7, 0
	v_or_b32_e32 v76, s4, v4
	v_mad_u64_u32 v[76:77], s[4:5], v76, s6, v[0:1]
	ds_read_b32 v87, v76
	v_cmp_gt_i32_e64 s[4:5], s0, v12
	v_cmp_lt_i32_e64 s[6:7], 63, v12
	s_waitcnt lgkmcnt(0)
	v_add_f32_e32 v6, 0, v80
	ds_write_b32 v2, v6
	v_add_f32_e32 v6, v6, v81
	ds_write_b32 v64, v6
	v_add_f32_e32 v6, v6, v82
	ds_write_b32 v66, v6
	v_add_f32_e32 v6, v6, v83
	ds_write_b32 v68, v6
	v_add_f32_e32 v6, v6, v84
	ds_write_b32 v70, v6 offset:1088
	v_add_f32_e32 v6, v6, v85
	ds_write_b32 v72, v6
	v_add_f32_e32 v6, v6, v86
	ds_write_b32 v74, v6
	v_add_f32_e32 v3, v6, v87
	ds_write_b32 v76, v3


; template <int TYPE>
; __device__ __forceinline__ void cumsum_g(int dir, LAS unsigned char* lds, int tid) {
;     ...
;     for (int ii = 0; ii < SEGL; ++ii) { const int i = seg * SEGL + (dir ? SEGL - 1 - ii : ii); run += G[i * C::LDG + d]; G[i * C::LDG + d] = run; }
;     SG[seg * 128 + d] = run;
;     __syncthreads();
;     float off = 0.f;
; #pragma unroll
;     for (int s = 0; s < NSEG; ++s) { const bool before = dir ? (s > seg) : (s < seg); if (before) off += SG[s * 128 + d]; }
	v_add_u32_e32 v2, s74, v5
	v_lshl_add_u32 v4, v1, 9, v2
	ds_write_b32 v4, v3
	v_cndmask_b32_e64 v3, 0, 1, s[6:7]
	v_cndmask_b32_e64 v4, 0, 1, s[4:5]
	v_cndmask_b32_e32 v3, v4, v3, vcc
	v_and_b32_e32 v3, 1, v3
	v_cmp_eq_u32_e64 s[4:5], 1, v3
	v_mov_b32_e32 v3, 0
	s_waitcnt lgkmcnt(0)
	s_barrier
	s_and_saveexec_b64 s[6:7], s[4:5]
	s_cbranch_execz .LBB0_290
	ds_read_b32 v3, v2
	s_waitcnt lgkmcnt(0)
	v_add_f32_e32 v3, 0, v3

; #define LAS __attribute__((address_space(3)))
; __device__ __forceinline__ float sigmoid_(float z) { return __builtin_amdgcn_rcpf(1.f + __expf(-z)); }
; template <int TYPE>
; __device__ __forceinline__ void lg_compute(const KArgs& a, unsigned char* wsb, int l, int h, int dir, const LgRaw& raw, LAS unsigned char* lds, int tid) {
;     ...
;     if constexpr (TYPE == 1) {
;         const float* lbp = (const float*)(wsb + WS_LB) + (dir * DEPTH + l) * 512 + h * 128;
;         const int d8 = tid & 15;
;         const f32x4 lb0 = *(const f32x4*)(lbp + d8 * 8), lb1 = *(const f32x4*)(lbp + d8 * 8 + 4);
;         const float lb[8] = {lb0[0], lb0[1], lb0[2], lb0[3], lb1[0], lb1[1], lb1[2], lb1[3]};
; #pragma unroll
;         for (int e2 = 0; e2 < 2; ++e2) { const int i = (tid >> 4) + 32 * e2;
;             float z[8], lg[8], kk[8]; unpack8(e2 ? raw.a1 : raw.a0, z);
; #pragma unroll
;             for (int e = 0; e < 8; ++e) { const float sg = sigmoid_(fmaxf(z[e], -80.f)); lg[e] = __logf(lb[e] + (1.f - lb[e]) * sg); kk[e] = (1.f - lb[e]) * (1.f - sg); }
;             *(LAS f32x4*)(G + i * C::LDG + d8 * 8) = (f32x4){lg[0], lg[1], lg[2], lg[3]}; *(LAS f32x4*)(G + i * C::LDG + d8 * 8 + 4) = (f32x4){lg[4], lg[5], lg[6], lg[7]};
;             *(LAS bf16x8*)(Kb + i * C::LDK_ + d8 * 8) = pack8(kk); }
.LBB0_498:
	s_lshl_b32 s54, s54, 10
	s_or_b32 s72, s54, s56
	v_lshl_add_u64 v[48:49], s[72:73], 2, v[86:87]
	global_load_dwordx4 v[52:55], v[48:49], off
	s_nop 0
	global_load_dwordx4 v[48:51], v[48:49], off offset:16
	v_lshlrev_b32_e32 v92, 16, v60
	v_lshlrev_b32_e32 v101, 16, v61
	v_and_b32_e32 v102, 0xffff0000, v61
	v_max_f32_e32 v61, v92, v92
	v_max_f32_e32 v61, 0xc2a00000, v61
	v_mul_f32_e32 v61, 0xbfb8aa3b, v61
	v_and_b32_e32 v60, 0xffff0000, v60
	v_exp_f32_e32 v61, v61
	v_max_f32_e32 v60, v60, v60
	v_max_f32_e32 v60, 0xc2a00000, v60
	v_mul_f32_e32 v60, 0xbfb8aa3b, v60
	v_add_f32_e32 v61, 1.0, v61
	v_exp_f32_e32 v60, v60
	v_lshlrev_b32_e32 v131, 16, v62
	v_and_b32_e32 v100, 0xffff0000, v62
	v_rcp_f32_e32 v62, v61
	v_add_f32_e32 v60, 1.0, v60
	v_lshlrev_b32_e32 v99, 16, v63
	v_and_b32_e32 v98, 0xffff0000, v63
	v_rcp_f32_e32 v63, v60
	v_max_f32_e32 v100, v100, v100
	v_max_f32_e32 v100, 0xc2a00000, v100
	v_mul_f32_e32 v100, 0xbfb8aa3b, v100
	v_pk_add_f32 v[94:95], v[62:63], 1.0 op_sel_hi:[1,0] neg_lo:[1,0] neg_hi:[1,0]
	v_exp_f32_e32 v100, v100
	v_max_f32_e32 v99, v99, v99
	v_max_f32_e32 v99, 0xc2a00000, v99
	v_mul_f32_e32 v99, 0xbfb8aa3b, v99
	v_add_f32_e32 v100, 1.0, v100
	v_rcp_f32_e32 v135, v100
	v_exp_f32_e32 v99, v99
	v_max_f32_e32 v98, v98, v98
	v_max_f32_e32 v98, 0xc2a00000, v98
	v_mul_f32_e32 v98, 0xbfb8aa3b, v98
	v_exp_f32_e32 v98, v98
	v_add_f32_e32 v99, 1.0, v99
	v_rcp_f32_e32 v138, v99
	v_add_f32_e32 v98, 1.0, v98
	v_rcp_f32_e32 v139, v98
	s_waitcnt vmcnt(0) lgkmcnt(0)
	v_pk_add_f32 v[92:93], v[52:53], 1.0 op_sel_hi:[1,0] neg_lo:[1,0] neg_hi:[1,0]
	s_nop 0
	v_fma_f32 v60, v92, v62, v52
	v_cmp_gt_f32_e32 vcc, s33, v60
	v_pk_mul_f32 v[96:97], v[92:93], v[94:95]
	v_pk_add_f32 v[94:95], v[54:55], 1.0 op_sel_hi:[1,0] neg_lo:[1,0] neg_hi:[1,0]
	v_cndmask_b32_e64 v61, 0, 32, vcc
	v_ldexp_f32 v60, v60, v61
	v_log_f32_e32 v60, v60
	v_pk_add_f32 v[98:99], v[50:51], 1.0 op_sel_hi:[1,0] neg_lo:[1,0] neg_hi:[1,0]
	v_pk_add_f32 v[140:141], v[138:139], 1.0 op_sel_hi:[1,0] neg_lo:[1,0] neg_hi:[1,0]
	v_mul_f32_e32 v61, 0x3f317217, v60
	v_fma_f32 v61, v60, s92, -v61
	v_fmac_f32_e32 v61, 0x3377d1cf, v60
	v_fmac_f32_e32 v61, 0x3f317217, v60
	v_cmp_lt_f32_e64 s[54:55], |v60|, s90
	v_pk_mul_f32 v[140:141], v[98:99], v[140:141]
	s_nop 0
	v_cndmask_b32_e64 v60, v60, v61, s[54:55]
	v_cndmask_b32_e32 v61, 0, v238, vcc
	v_sub_f32_e32 v60, v60, v61
	v_fma_f32 v61, v93, v63, v53
	v_cmp_gt_f32_e32 vcc, s33, v61
	s_nop 1
	v_cndmask_b32_e64 v62, 0, 32, vcc
	v_ldexp_f32 v61, v61, v62
	v_log_f32_e32 v61, v61
	s_nop 0
	v_mul_f32_e32 v62, 0x3f317217, v61
	v_fma_f32 v62, v61, s92, -v62
	v_fmac_f32_e32 v62, 0x3377d1cf, v61
	v_fmac_f32_e32 v62, 0x3f317217, v61
	v_cmp_lt_f32_e64 s[54:55], |v61|, s90
	s_nop 1
	v_cndmask_b32_e64 v61, v61, v62, s[54:55]
	v_cndmask_b32_e32 v62, 0, v238, vcc
	v_sub_f32_e32 v61, v61, v62
	v_max_f32_e32 v62, v101, v101
	v_max_f32_e32 v62, 0xc2a00000, v62
	v_mul_f32_e32 v62, 0xbfb8aa3b, v62
	v_exp_f32_e32 v62, v62
	s_nop 0
	v_add_f32_e32 v62, 1.0, v62
	v_rcp_f32_e32 v132, v62
	v_max_f32_e32 v62, v102, v102
	v_max_f32_e32 v62, 0xc2a00000, v62
	v_mul_f32_e32 v62, 0xbfb8aa3b, v62
	v_exp_f32_e32 v62, v62
	s_nop 0
	v_add_f32_e32 v62, 1.0, v62
	v_rcp_f32_e32 v133, v62
	v_fma_f32 v62, v94, v132, v54
	v_cmp_gt_f32_e32 vcc, s33, v62
	v_pk_add_f32 v[102:103], v[132:133], 1.0 op_sel_hi:[1,0] neg_lo:[1,0] neg_hi:[1,0]
	s_nop 0
	v_cndmask_b32_e64 v63, 0, 32, vcc
	v_ldexp_f32 v62, v62, v63
	v_log_f32_e32 v62, v62
	v_pk_mul_f32 v[102:103], v[94:95], v[102:103]
	v_mul_f32_e32 v63, 0x3f317217, v62
	v_fma_f32 v63, v62, s92, -v63
	v_fmac_f32_e32 v63, 0x3377d1cf, v62
	v_fmac_f32_e32 v63, 0x3f317217, v62
	v_cmp_lt_f32_e64 s[54:55], |v62|, s90
	s_nop 1
	v_cndmask_b32_e64 v62, v62, v63, s[54:55]
	v_cndmask_b32_e32 v63, 0, v238, vcc
	v_sub_f32_e32 v62, v62, v63
	v_fma_f32 v63, v95, v133, v55
	v_cmp_gt_f32_e32 vcc, s33, v63
	s_nop 1
	v_cndmask_b32_e64 v101, 0, 32, vcc
	v_ldexp_f32 v63, v63, v101
	v_log_f32_e32 v63, v63
	s_nop 0
	v_mul_f32_e32 v101, 0x3f317217, v63
	v_fma_f32 v101, v63, s92, -v101
	v_fmac_f32_e32 v101, 0x3377d1cf, v63
	v_fmac_f32_e32 v101, 0x3f317217, v63
	v_cmp_lt_f32_e64 s[54:55], |v63|, s90
	s_nop 1
	v_cndmask_b32_e64 v63, v63, v101, s[54:55]
	v_cndmask_b32_e32 v101, 0, v238, vcc
	v_sub_f32_e32 v63, v63, v101
	v_max_f32_e32 v101, v131, v131
	v_max_f32_e32 v101, 0xc2a00000, v101
	v_mul_f32_e32 v101, 0xbfb8aa3b, v101
	v_exp_f32_e32 v101, v101
	s_nop 0
	v_add_f32_e32 v101, 1.0, v101
	v_rcp_f32_e32 v134, v101
	v_pk_add_f32 v[100:101], v[48:49], 1.0 op_sel_hi:[1,0] neg_lo:[1,0] neg_hi:[1,0]
	v_pk_add_f32 v[136:137], v[134:135], 1.0 op_sel_hi:[1,0] neg_lo:[1,0] neg_hi:[1,0]
	v_fma_f32 v131, v100, v134, v48
	v_cmp_gt_f32_e32 vcc, s33, v131
	v_pk_mul_f32 v[136:137], v[100:101], v[136:137]
	s_nop 0
	v_cndmask_b32_e64 v132, 0, 32, vcc
	v_ldexp_f32 v131, v131, v132
	v_log_f32_e32 v131, v131
	s_nop 0
	v_mul_f32_e32 v132, 0x3f317217, v131
	v_fma_f32 v132, v131, s92, -v132
	v_fmac_f32_e32 v132, 0x3377d1cf, v131
	v_fmac_f32_e32 v132, 0x3f317217, v131
	v_cmp_lt_f32_e64 s[54:55], |v131|, s90
	s_nop 1
	v_cndmask_b32_e64 v131, v131, v132, s[54:55]
	v_cndmask_b32_e32 v132, 0, v238, vcc
	v_sub_f32_e32 v132, v131, v132
	v_fma_f32 v131, v101, v135, v49
	v_cmp_gt_f32_e32 vcc, s33, v131
	s_nop 1
	v_cndmask_b32_e64 v133, 0, 32, vcc
	v_ldexp_f32 v131, v131, v133
	v_log_f32_e32 v131, v131
	s_nop 0
	v_mul_f32_e32 v133, 0x3f317217, v131
	v_fma_f32 v133, v131, s92, -v133
	v_fmac_f32_e32 v133, 0x3377d1cf, v131
	v_fmac_f32_e32 v133, 0x3f317217, v131
	v_cmp_lt_f32_e64 s[54:55], |v131|, s90
	s_nop 1
	v_cndmask_b32_e64 v131, v131, v133, s[54:55]
	v_cndmask_b32_e32 v133, 0, v238, vcc
; #define LAS __attribute__((address_space(3)))
; __device__ __forceinline__ float sigmoid_(float z) { return __builtin_amdgcn_rcpf(1.f + __expf(-z)); }
; template <int TYPE>
; __device__ __forceinline__ void lg_compute(const KArgs& a, unsigned char* wsb, int l, int h, int dir, const LgRaw& raw, LAS unsigned char* lds, int tid) {
;     ...
; #pragma unroll
;         for (int e2 = 0; e2 < 2; ++e2) { const int i = (tid >> 4) + 32 * e2;
;             float z[8], lg[8], kk[8]; unpack8(e2 ? raw.a1 : raw.a0, z);
; #pragma unroll
;             for (int e = 0; e < 8; ++e) { const float sg = sigmoid_(fmaxf(z[e], -80.f)); lg[e] = __logf(lb[e] + (1.f - lb[e]) * sg); kk[e] = (1.f - lb[e]) * (1.f - sg); }
;             *(LAS f32x4*)(G + i * C::LDG + d8 * 8) = (f32x4){lg[0], lg[1], lg[2], lg[3]}; *(LAS f32x4*)(G + i * C::LDG + d8 * 8 + 4) = (f32x4){lg[4], lg[5], lg[6], lg[7]};
;             *(LAS bf16x8*)(Kb + i * C::LDK_ + d8 * 8) = pack8(kk); }
	v_sub_f32_e32 v133, v131, v133
	v_fma_f32 v131, v98, v138, v50
	v_cmp_gt_f32_e32 vcc, s33, v131
	s_nop 1
	v_cndmask_b32_e64 v134, 0, 32, vcc
	v_ldexp_f32 v131, v131, v134
	v_log_f32_e32 v131, v131
	s_nop 0
	v_mul_f32_e32 v134, 0x3f317217, v131
	v_fma_f32 v134, v131, s92, -v134
	v_fmac_f32_e32 v134, 0x3377d1cf, v131
	v_fmac_f32_e32 v134, 0x3f317217, v131
	v_cmp_lt_f32_e64 s[54:55], |v131|, s90
	s_nop 1
	v_cndmask_b32_e64 v131, v131, v134, s[54:55]
	v_cndmask_b32_e32 v134, 0, v238, vcc
	v_sub_f32_e32 v134, v131, v134
	v_fma_f32 v131, v99, v139, v51
	v_cmp_gt_f32_e32 vcc, s33, v131
	s_nop 1
	v_cndmask_b32_e64 v135, 0, 32, vcc
	v_ldexp_f32 v131, v131, v135
	v_log_f32_e32 v131, v131
	s_nop 0
	v_mul_f32_e32 v135, 0x3f317217, v131
	v_fma_f32 v135, v131, s92, -v135
	v_fmac_f32_e32 v135, 0x3377d1cf, v131
	v_fmac_f32_e32 v135, 0x3f317217, v131
	v_cmp_lt_f32_e64 s[54:55], |v131|, s90
	s_nop 1
	v_cndmask_b32_e64 v131, v131, v135, s[54:55]
	v_cndmask_b32_e32 v135, 0, v238, vcc
	v_sub_f32_e32 v135, v131, v135
	ds_write_b128 v125, v[60:63]
	ds_write_b128 v125, v[132:135] offset:16
	v_cvt_pk_bf16_f32 v60, v96, v97
	v_cvt_pk_bf16_f32 v61, v102, v103
	v_cvt_pk_bf16_f32 v62, v136, v137
	v_cvt_pk_bf16_f32 v63, v140, v141
	ds_write_b128 v126, v[60:63] offset:33792
	v_lshlrev_b32_e32 v62, 16, v56
	v_and_b32_e32 v63, 0xffff0000, v56
	v_max_f32_e32 v56, v62, v62
	v_max_f32_e32 v56, 0xc2a00000, v56
	v_mul_f32_e32 v56, 0xbfb8aa3b, v56
	v_exp_f32_e32 v56, v56
	v_lshlrev_b32_e32 v96, 16, v57
	v_and_b32_e32 v97, 0xffff0000, v57
	v_lshlrev_b32_e32 v102, 16, v58
	v_add_f32_e32 v56, 1.0, v56
	v_rcp_f32_e32 v56, v56
	v_and_b32_e32 v103, 0xffff0000, v58
	v_lshlrev_b32_e32 v61, 16, v59
	v_and_b32_e32 v60, 0xffff0000, v59
	v_fma_f32 v52, v92, v56, v52
	v_cmp_gt_f32_e32 vcc, s33, v52
	v_max_f32_e32 v61, v61, v61
	v_max_f32_e32 v61, 0xc2a00000, v61
	v_cndmask_b32_e64 v57, 0, 32, vcc
	v_ldexp_f32 v52, v52, v57
	v_log_f32_e32 v52, v52
	v_mul_f32_e32 v61, 0xbfb8aa3b, v61
	v_exp_f32_e32 v61, v61
	v_max_f32_e32 v60, v60, v60
	v_mul_f32_e32 v57, 0x3f317217, v52
	v_fma_f32 v57, v52, s92, -v57
	v_fmac_f32_e32 v57, 0x3377d1cf, v52
	v_fmac_f32_e32 v57, 0x3f317217, v52
	v_cmp_lt_f32_e64 s[54:55], |v52|, s90
	v_add_f32_e32 v61, 1.0, v61
	v_max_f32_e32 v60, 0xc2a00000, v60
	v_cndmask_b32_e64 v52, v52, v57, s[54:55]
	v_cndmask_b32_e32 v57, 0, v238, vcc
	v_sub_f32_e32 v52, v52, v57
	v_max_f32_e32 v57, v63, v63
	v_max_f32_e32 v57, 0xc2a00000, v57
	v_mul_f32_e32 v57, 0xbfb8aa3b, v57
	v_exp_f32_e32 v57, v57
	v_mul_f32_e32 v60, 0xbfb8aa3b, v60
	v_exp_f32_e32 v60, v60
	v_add_f32_e32 v57, 1.0, v57
	v_rcp_f32_e32 v57, v57
	v_add_f32_e32 v60, 1.0, v60
	v_fma_f32 v53, v93, v57, v53
	v_cmp_gt_f32_e32 vcc, s33, v53
	v_pk_add_f32 v[56:57], v[56:57], 1.0 op_sel_hi:[1,0] neg_lo:[1,0] neg_hi:[1,0]
	s_nop 0
	v_cndmask_b32_e64 v58, 0, 32, vcc
	v_ldexp_f32 v53, v53, v58
	v_log_f32_e32 v53, v53
	v_pk_mul_f32 v[56:57], v[92:93], v[56:57]
	v_rcp_f32_e32 v93, v60
	v_mul_f32_e32 v58, 0x3f317217, v53
	v_fma_f32 v58, v53, s92, -v58
	v_fmac_f32_e32 v58, 0x3377d1cf, v53
	v_fmac_f32_e32 v58, 0x3f317217, v53
	v_cmp_lt_f32_e64 s[54:55], |v53|, s90
	v_fmac_f32_e32 v51, v99, v93
	s_nop 0
	v_cndmask_b32_e64 v53, v53, v58, s[54:55]
	v_cndmask_b32_e32 v58, 0, v238, vcc
	v_sub_f32_e32 v53, v53, v58
	v_max_f32_e32 v58, v96, v96
	v_max_f32_e32 v58, 0xc2a00000, v58
	v_mul_f32_e32 v58, 0xbfb8aa3b, v58
	v_exp_f32_e32 v58, v58
	s_nop 0
	v_add_f32_e32 v58, 1.0, v58
	v_rcp_f32_e32 v58, v58
	s_nop 0
	v_fma_f32 v54, v94, v58, v54
	v_cmp_gt_f32_e32 vcc, s33, v54
	s_nop 1
	v_cndmask_b32_e64 v59, 0, 32, vcc
	v_ldexp_f32 v54, v54, v59
	v_log_f32_e32 v54, v54
	s_nop 0
	v_mul_f32_e32 v59, 0x3f317217, v54
	v_fma_f32 v59, v54, s92, -v59
	v_fmac_f32_e32 v59, 0x3377d1cf, v54
	v_fmac_f32_e32 v59, 0x3f317217, v54
	v_cmp_lt_f32_e64 s[54:55], |v54|, s90
	s_nop 1
	v_cndmask_b32_e64 v54, v54, v59, s[54:55]
	v_cndmask_b32_e32 v59, 0, v238, vcc
	v_sub_f32_e32 v54, v54, v59
	v_max_f32_e32 v59, v97, v97
	v_max_f32_e32 v59, 0xc2a00000, v59
	v_mul_f32_e32 v59, 0xbfb8aa3b, v59
	v_exp_f32_e32 v59, v59
	s_nop 0
	v_add_f32_e32 v59, 1.0, v59
	v_rcp_f32_e32 v59, v59
	s_nop 0
	v_fmac_f32_e32 v55, v95, v59
	v_cmp_gt_f32_e32 vcc, s33, v55
	v_pk_add_f32 v[58:59], v[58:59], 1.0 op_sel_hi:[1,0] neg_lo:[1,0] neg_hi:[1,0]
	s_nop 0
	v_cndmask_b32_e64 v62, 0, 32, vcc
	v_ldexp_f32 v55, v55, v62
	v_log_f32_e32 v55, v55
	v_pk_mul_f32 v[58:59], v[94:95], v[58:59]
	v_mul_f32_e32 v62, 0x3f317217, v55
	v_fma_f32 v62, v55, s92, -v62
	v_fmac_f32_e32 v62, 0x3377d1cf, v55
	v_fmac_f32_e32 v62, 0x3f317217, v55
	v_cmp_lt_f32_e64 s[54:55], |v55|, s90
	s_nop 1
	v_cndmask_b32_e64 v55, v55, v62, s[54:55]
	v_cndmask_b32_e32 v62, 0, v238, vcc
	v_sub_f32_e32 v55, v55, v62
	v_max_f32_e32 v62, v102, v102
	v_max_f32_e32 v62, 0xc2a00000, v62
	v_mul_f32_e32 v62, 0xbfb8aa3b, v62
	v_exp_f32_e32 v62, v62
	s_nop 0
	v_add_f32_e32 v62, 1.0, v62
	v_rcp_f32_e32 v62, v62
	s_nop 0
	v_fma_f32 v48, v100, v62, v48
	v_cmp_gt_f32_e32 vcc, s33, v48
	s_nop 1
	v_cndmask_b32_e64 v63, 0, 32, vcc
	v_ldexp_f32 v48, v48, v63
	v_log_f32_e32 v48, v48
	s_nop 0
; #define LAS __attribute__((address_space(3)))
; __device__ __forceinline__ float sigmoid_(float z) { return __builtin_amdgcn_rcpf(1.f + __expf(-z)); }
; template <int TYPE>
; __device__ __forceinline__ void lg_compute(const KArgs& a, unsigned char* wsb, int l, int h, int dir, const LgRaw& raw, LAS unsigned char* lds, int tid) {
;     ...
;         for (int e2 = 0; e2 < 2; ++e2) { const int i = (tid >> 4) + 32 * e2;
;             float z[8], lg[8], kk[8]; unpack8(e2 ? raw.a1 : raw.a0, z);
; #pragma unroll
;             for (int e = 0; e < 8; ++e) { const float sg = sigmoid_(fmaxf(z[e], -80.f)); lg[e] = __logf(lb[e] + (1.f - lb[e]) * sg); kk[e] = (1.f - lb[e]) * (1.f - sg); }
;             *(LAS f32x4*)(G + i * C::LDG + d8 * 8) = (f32x4){lg[0], lg[1], lg[2], lg[3]}; *(LAS f32x4*)(G + i * C::LDG + d8 * 8 + 4) = (f32x4){lg[4], lg[5], lg[6], lg[7]};
;             *(LAS bf16x8*)(Kb + i * C::LDK_ + d8 * 8) = pack8(kk); }
; template <int TYPE>
; __device__ __forceinline__ void cumsum_g(int dir, LAS unsigned char* lds, int tid) {
;     using C = Cfg<TYPE>; constexpr int NSEG = 512 / C::DK, SEGL = 64 / NSEG;
;     LAS float* G = (LAS float*)(lds + SC_G); LAS float* SG = (LAS float*)(lds + SC_SEG);
;     const int d = tid % C::DK, seg = tid / C::DK;
;     __syncthreads();
;     float run = 0.f;
; #pragma unroll
;     for (int ii = 0; ii < SEGL; ++ii) { const int i = seg * SEGL + (dir ? SEGL - 1 - ii : ii); run += G[i * C::LDG + d]; G[i * C::LDG + d] = run; }
;     SG[seg * 128 + d] = run;
;     __syncthreads();
	v_mul_f32_e32 v63, 0x3f317217, v48
	v_fma_f32 v63, v48, s92, -v63
	v_fmac_f32_e32 v63, 0x3377d1cf, v48
	v_fmac_f32_e32 v63, 0x3f317217, v48
	v_cmp_lt_f32_e64 s[54:55], |v48|, s90
	s_nop 1
	v_cndmask_b32_e64 v48, v48, v63, s[54:55]
	v_cndmask_b32_e32 v63, 0, v238, vcc
	v_sub_f32_e32 v48, v48, v63
	v_max_f32_e32 v63, v103, v103
	v_max_f32_e32 v63, 0xc2a00000, v63
	v_mul_f32_e32 v63, 0xbfb8aa3b, v63
	v_exp_f32_e32 v63, v63
	s_nop 0
	v_add_f32_e32 v63, 1.0, v63
	v_rcp_f32_e32 v63, v63
	s_nop 0
	v_fma_f32 v49, v101, v63, v49
	v_cmp_gt_f32_e32 vcc, s33, v49
	v_pk_add_f32 v[62:63], v[62:63], 1.0 op_sel_hi:[1,0] neg_lo:[1,0] neg_hi:[1,0]
	s_nop 0
	v_cndmask_b32_e64 v92, 0, 32, vcc
	v_ldexp_f32 v49, v49, v92
	v_log_f32_e32 v49, v49
	v_pk_mul_f32 v[62:63], v[100:101], v[62:63]
	v_mul_f32_e32 v92, 0x3f317217, v49
	v_fma_f32 v92, v49, s92, -v92
	v_fmac_f32_e32 v92, 0x3377d1cf, v49
	v_fmac_f32_e32 v92, 0x3f317217, v49
	v_cmp_lt_f32_e64 s[54:55], |v49|, s90
	s_nop 1
	v_cndmask_b32_e64 v49, v49, v92, s[54:55]
	v_cndmask_b32_e32 v92, 0, v238, vcc
	v_sub_f32_e32 v49, v49, v92
	v_rcp_f32_e32 v92, v61
	s_nop 0
	v_fma_f32 v50, v98, v92, v50
	v_cmp_gt_f32_e32 vcc, s33, v50
	s_nop 1
	v_cndmask_b32_e64 v61, 0, 32, vcc
	v_ldexp_f32 v50, v50, v61
	v_log_f32_e32 v50, v50
	s_nop 0
	v_mul_f32_e32 v61, 0x3f317217, v50
	v_fma_f32 v61, v50, s92, -v61
	v_fmac_f32_e32 v61, 0x3377d1cf, v50
	v_fmac_f32_e32 v61, 0x3f317217, v50
	v_cmp_lt_f32_e64 s[54:55], |v50|, s90
	s_nop 1
	v_cndmask_b32_e64 v50, v50, v61, s[54:55]
	v_cndmask_b32_e32 v61, 0, v238, vcc
	v_cmp_gt_f32_e32 vcc, s33, v51
	v_sub_f32_e32 v50, v50, v61
	s_nop 0
	v_cndmask_b32_e64 v60, 0, 32, vcc
	v_ldexp_f32 v51, v51, v60
	v_log_f32_e32 v51, v51
	s_nop 0
	v_mul_f32_e32 v60, 0x3f317217, v51
	v_fma_f32 v60, v51, s92, -v60
	v_fmac_f32_e32 v60, 0x3377d1cf, v51
	v_fmac_f32_e32 v60, 0x3f317217, v51
	v_cmp_lt_f32_e64 s[54:55], |v51|, s90
	s_nop 1
	v_cndmask_b32_e64 v51, v51, v60, s[54:55]
	v_cndmask_b32_e32 v60, 0, v238, vcc
	v_sub_f32_e32 v51, v51, v60
	v_pk_add_f32 v[60:61], v[92:93], 1.0 op_sel_hi:[1,0] neg_lo:[1,0] neg_hi:[1,0]
	ds_write_b128 v125, v[52:55] offset:16896
	ds_write_b128 v125, v[48:51] offset:16912
	v_pk_mul_f32 v[60:61], v[98:99], v[60:61]
	v_cvt_pk_bf16_f32 v48, v56, v57
	v_cvt_pk_bf16_f32 v49, v58, v59
	v_cvt_pk_bf16_f32 v50, v62, v63
	v_cvt_pk_bf16_f32 v51, v60, v61
	ds_write_b128 v126, v[48:51] offset:42496
	v_or_b32_e32 v48, s95, v105
	v_mad_u64_u32 v[48:49], s[54:55], v48, s91, v[88:89]
	s_waitcnt lgkmcnt(0)
	s_barrier
	ds_read_b32 v174, v48
	v_or_b32_e32 v142, s87, v105
	v_mad_u64_u32 v[142:143], s[54:55], v142, s91, v[88:89]
	ds_read_b32 v175, v142
	v_or_b32_e32 v144, s86, v105
	v_mad_u64_u32 v[144:145], s[54:55], v144, s91, v[88:89]
	ds_read_b32 v176, v144
	v_or_b32_e32 v146, s85, v105
	v_mad_u64_u32 v[146:147], s[54:55], v146, s91, v[88:89]
	ds_read_b32 v177, v146
	v_or_b32_e32 v148, s84, v105
	v_mad_u64_u32 v[148:149], s[54:55], v148, s91, v[88:89]
	ds_read_b32 v178, v148
	v_or_b32_e32 v150, s83, v105
	v_mad_u64_u32 v[150:151], s[54:55], v150, s91, v[88:89]
	ds_read_b32 v179, v150
	v_or_b32_e32 v152, s82, v105
	v_mad_u64_u32 v[152:153], s[54:55], v152, s91, v[88:89]
	ds_read_b32 v180, v152
	v_or_b32_e32 v154, s81, v105
	v_mad_u64_u32 v[154:155], s[54:55], v154, s91, v[88:89]
	ds_read_b32 v181, v154
	v_or_b32_e32 v156, s77, v105
	v_mad_u64_u32 v[156:157], s[54:55], v156, s91, v[88:89]
	ds_read_b32 v182, v156
	v_or_b32_e32 v158, s80, v105
	v_mad_u64_u32 v[158:159], s[54:55], v158, s91, v[88:89]
	ds_read_b32 v183, v158
	v_or_b32_e32 v160, s79, v105
	v_mad_u64_u32 v[160:161], s[54:55], v160, s91, v[88:89]
	ds_read_b32 v184, v160
	v_or_b32_e32 v162, s78, v105
	v_mad_u64_u32 v[162:163], s[54:55], v162, s91, v[88:89]
	ds_read_b32 v185, v162
	v_or_b32_e32 v164, s76, v105
	v_mad_u64_u32 v[164:165], s[54:55], v164, s91, v[88:89]
	ds_read_b32 v186, v164
	v_or_b32_e32 v166, s75, v105
	v_mad_u64_u32 v[166:167], s[54:55], v166, s91, v[88:89]
	ds_read_b32 v187, v166
	v_or_b32_e32 v168, s74, v105
	v_mad_u64_u32 v[168:169], s[54:55], v168, s91, v[88:89]
	ds_read_b32 v188, v168
	v_or_b32_e32 v170, s71, v105
	v_mad_u64_u32 v[170:171], s[54:55], v170, s91, v[88:89]
	ds_read_b32 v189, v170
	s_waitcnt lgkmcnt(0)
	v_add_f32_e32 v50, 0, v174
	ds_write_b32 v48, v50
	v_add_f32_e32 v50, v50, v175
	ds_write_b32 v142, v50
	v_add_f32_e32 v50, v50, v176
	ds_write_b32 v144, v50
	v_add_f32_e32 v50, v50, v177
	ds_write_b32 v146, v50
	v_add_f32_e32 v50, v50, v178
	ds_write_b32 v148, v50
	v_add_f32_e32 v50, v50, v179
	ds_write_b32 v150, v50
	v_add_f32_e32 v50, v50, v180
	ds_write_b32 v152, v50
	v_add_f32_e32 v50, v50, v181
	ds_write_b32 v154, v50
	v_add_f32_e32 v50, v50, v182
	ds_write_b32 v156, v50
	v_add_f32_e32 v50, v50, v183
	ds_write_b32 v158, v50
	v_add_f32_e32 v50, v50, v184
	ds_write_b32 v160, v50
	v_add_f32_e32 v50, v50, v185
	ds_write_b32 v162, v50
	v_add_f32_e32 v50, v50, v186
	ds_write_b32 v164, v50
	v_add_f32_e32 v50, v50, v187
	ds_write_b32 v166, v50
	v_add_f32_e32 v50, v50, v188
	ds_write_b32 v168, v50
	v_add_f32_e32 v49, v50, v189
	ds_write_b32 v170, v49


; template <int TYPE>
; __device__ __forceinline__ void cumsum_g(int dir, LAS unsigned char* lds, int tid) {
;     ...
;     for (int ii = 0; ii < SEGL; ++ii) { const int i = seg * SEGL + (dir ? SEGL - 1 - ii : ii); run += G[i * C::LDG + d]; G[i * C::LDG + d] = run; }
;     SG[seg * 128 + d] = run;
;     __syncthreads();
;     float off = 0.f;
; #pragma unroll
;     for (int s = 0; s < NSEG; ++s) { const bool before = dir ? (s > seg) : (s < seg); if (before) off += SG[s * 128 + d]; }
	ds_write_b32 v104, v49
	v_mov_b32_e32 v48, 0
	s_waitcnt lgkmcnt(0)
	s_barrier
	s_and_saveexec_b64 s[54:55], s[68:69]
	s_cbranch_execz .LBB0_500
	ds_read_b32 v48, v106
	s_waitcnt lgkmcnt(0)
	v_add_f32_e32 v48, 0, v48

; template <int TYPE>
; __device__ __forceinline__ void lg_compute(const KArgs& a, unsigned char* wsb, int l, int h, int dir, const LgRaw& raw, LAS unsigned char* lds, int tid) {
;     ...
;     } else {
;         const int i = tid >> 3, d8 = tid & 7;
;         float ua[16]; unpack8(raw.a0, ua); unpack8(raw.a1, ua + 8);
;         const float* up = (const float*)a.in[3] + (size_t)((l * 2 + dir) * 16) * 256 + h * 64 + d8 * 8;
;         const float* bs = (const float*)a.in[4] + (l * 2 + dir) * 256 + h * 64 + d8 * 8;
;         f32x4 z0 = *(const f32x4*)bs, z1 = *(const f32x4*)(bs + 4);
; #pragma unroll
;         for (int r = 0; r < 16; ++r) { z0 += ua[r] * *(const f32x4*)(up + r * 256); z1 += ua[r] * *(const f32x4*)(up + r * 256 + 4); }
.LBB0_515:
	s_or_b32 s70, s70, s5
	s_lshl_b32 s72, s70, 12
	v_lshlrev_b32_e32 v92, 16, v50
	v_and_b32_e32 v88, 0xffff0000, v50
	v_lshlrev_b32_e32 v86, 16, v51
	v_and_b32_e32 v84, 0xffff0000, v51
	v_lshl_add_u64 v[50:51], s[72:73], 2, v[70:71]
	s_lshl_b32 s72, s70, 8
	v_lshl_add_u64 v[120:121], s[72:73], 2, v[72:73]
	global_load_dwordx4 v[116:119], v[120:121], off offset:16
	s_nop 0
	global_load_dwordx4 v[120:123], v[120:121], off
	s_nop 0
	global_load_dwordx4 v[124:127], v[50:51], off offset:16
	global_load_dwordx4 v[128:131], v[50:51], off
	v_lshlrev_b32_e32 v90, 16, v48
	v_and_b32_e32 v132, 0xffff0000, v48
	v_lshlrev_b32_e32 v134, 16, v49
	v_and_b32_e32 v136, 0xffff0000, v49
	s_mov_b64 s[70:71], 0x1000
	v_lshlrev_b32_e32 v82, 16, v44
	v_and_b32_e32 v80, 0xffff0000, v44
	v_lshlrev_b32_e32 v78, 16, v45
	v_and_b32_e32 v76, 0xffff0000, v45
	v_lshlrev_b32_e32 v48, 16, v46
	v_and_b32_e32 v46, 0xffff0000, v46
	v_lshlrev_b32_e32 v44, 16, v47
	v_and_b32_e32 v74, 0xffff0000, v47
	s_mov_b32 s72, 0xbfb8aa3b
	s_mov_b32 s9, 0x7f800000
	s_mov_b32 s8, 0x3d800000
	s_waitcnt vmcnt(0)
	v_pk_fma_f32 v[124:125], v[124:125], v[90:91], v[116:117] op_sel_hi:[1,0,1]
	v_pk_fma_f32 v[130:131], v[130:131], v[90:91], v[122:123] op_sel_hi:[1,0,1]
	v_pk_fma_f32 v[128:129], v[128:129], v[90:91], v[120:121] op_sel_hi:[1,0,1]
	v_pk_fma_f32 v[90:91], v[126:127], v[90:91], v[118:119] op_sel_hi:[1,0,1]
	global_load_dwordx4 v[116:119], v[50:51], off offset:1040
	global_load_dwordx4 v[120:123], v[50:51], off offset:1024
	s_waitcnt vmcnt(0)
	v_pk_fma_f32 v[90:91], v[132:133], v[118:119], v[90:91] op_sel_hi:[0,1,1]
	v_pk_fma_f32 v[126:127], v[132:133], v[120:121], v[128:129] op_sel_hi:[0,1,1]
	v_pk_fma_f32 v[128:129], v[132:133], v[122:123], v[130:131] op_sel_hi:[0,1,1]
	v_pk_fma_f32 v[124:125], v[132:133], v[116:117], v[124:125] op_sel_hi:[0,1,1]
	global_load_dwordx4 v[116:119], v[50:51], off offset:2064
	global_load_dwordx4 v[120:123], v[50:51], off offset:2048
	v_add_co_u32_e32 v132, vcc, s77, v50
	s_waitcnt vmcnt(0)
	v_pk_fma_f32 v[124:125], v[134:135], v[116:117], v[124:125] op_sel_hi:[0,1,1]
	v_pk_fma_f32 v[128:129], v[134:135], v[122:123], v[128:129] op_sel_hi:[0,1,1]
	v_pk_fma_f32 v[126:127], v[134:135], v[120:121], v[126:127] op_sel_hi:[0,1,1]
	v_pk_fma_f32 v[90:91], v[134:135], v[118:119], v[90:91] op_sel_hi:[0,1,1]
	global_load_dwordx4 v[116:119], v[50:51], off offset:3088
	global_load_dwordx4 v[120:123], v[50:51], off offset:3072
	v_addc_co_u32_e32 v133, vcc, 0, v51, vcc
	s_waitcnt vmcnt(0)
	v_pk_fma_f32 v[130:131], v[136:137], v[118:119], v[90:91] op_sel_hi:[0,1,1]
	v_pk_fma_f32 v[126:127], v[136:137], v[120:121], v[126:127] op_sel_hi:[0,1,1]
	v_lshl_add_u64 v[120:121], v[50:51], 0, s[70:71]
	s_movk_i32 s70, 0x2000
	v_add_co_u32_e32 v90, vcc, s70, v50
	v_pk_fma_f32 v[128:129], v[136:137], v[122:123], v[128:129] op_sel_hi:[0,1,1]
	s_nop 0
	v_addc_co_u32_e32 v91, vcc, 0, v51, vcc
	v_pk_fma_f32 v[124:125], v[136:137], v[116:117], v[124:125] op_sel_hi:[0,1,1]
	global_load_dwordx4 v[116:119], v[90:91], off offset:-4096
	s_nop 0
	global_load_dwordx4 v[120:123], v[120:121], off offset:16
	s_mov_b64 s[70:71], 0x1400
	s_waitcnt vmcnt(0)
	v_pk_fma_f32 v[128:129], v[92:93], v[118:119], v[128:129] op_sel_hi:[0,1,1]
	v_pk_fma_f32 v[124:125], v[92:93], v[120:121], v[124:125] op_sel_hi:[0,1,1]
	v_lshl_add_u64 v[120:121], v[50:51], 0, s[70:71]
	v_pk_fma_f32 v[126:127], v[92:93], v[116:117], v[126:127] op_sel_hi:[0,1,1]
	v_pk_fma_f32 v[130:131], v[92:93], v[122:123], v[130:131] op_sel_hi:[0,1,1]
	global_load_dwordx4 v[116:119], v[132:133], off offset:1024
	s_nop 0
	global_load_dwordx4 v[120:123], v[120:121], off offset:16
	s_mov_b64 s[70:71], 0x1800
	s_waitcnt vmcnt(0)
	v_pk_fma_f32 v[128:129], v[88:89], v[118:119], v[128:129] op_sel_hi:[0,1,1]
	v_pk_fma_f32 v[124:125], v[88:89], v[120:121], v[124:125] op_sel_hi:[0,1,1]
	v_lshl_add_u64 v[120:121], v[50:51], 0, s[70:71]
	v_pk_fma_f32 v[126:127], v[88:89], v[116:117], v[126:127] op_sel_hi:[0,1,1]
	v_pk_fma_f32 v[130:131], v[88:89], v[122:123], v[130:131] op_sel_hi:[0,1,1]
	global_load_dwordx4 v[116:119], v[132:133], off offset:2048
	s_nop 0
	global_load_dwordx4 v[120:123], v[120:121], off offset:16
	s_mov_b64 s[70:71], 0x1c00
	s_waitcnt vmcnt(0)
	v_pk_fma_f32 v[128:129], v[86:87], v[118:119], v[128:129] op_sel_hi:[0,1,1]
	v_pk_fma_f32 v[124:125], v[86:87], v[120:121], v[124:125] op_sel_hi:[0,1,1]
	v_lshl_add_u64 v[120:121], v[50:51], 0, s[70:71]
	v_pk_fma_f32 v[126:127], v[86:87], v[116:117], v[126:127] op_sel_hi:[0,1,1]
	v_pk_fma_f32 v[130:131], v[86:87], v[122:123], v[130:131] op_sel_hi:[0,1,1]
	global_load_dwordx4 v[116:119], v[132:133], off offset:3072
	s_nop 0
	global_load_dwordx4 v[120:123], v[120:121], off offset:16
	s_mov_b64 s[70:71], 0x2000
	s_waitcnt vmcnt(0)
	v_pk_fma_f32 v[128:129], v[84:85], v[118:119], v[128:129] op_sel_hi:[0,1,1]
	v_pk_fma_f32 v[124:125], v[84:85], v[120:121], v[124:125] op_sel_hi:[0,1,1]
	v_lshl_add_u64 v[120:121], v[50:51], 0, s[70:71]
	v_pk_fma_f32 v[126:127], v[84:85], v[116:117], v[126:127] op_sel_hi:[0,1,1]
	v_pk_fma_f32 v[130:131], v[84:85], v[122:123], v[130:131] op_sel_hi:[0,1,1]
	global_load_dwordx4 v[116:119], v[90:91], off
	s_nop 0
	global_load_dwordx4 v[120:123], v[120:121], off offset:16
	s_mov_b64 s[70:71], 0x2400
	s_waitcnt vmcnt(0)
	v_pk_fma_f32 v[128:129], v[82:83], v[118:119], v[128:129] op_sel_hi:[0,1,1]
	v_pk_fma_f32 v[124:125], v[82:83], v[120:121], v[124:125] op_sel_hi:[0,1,1]
	v_lshl_add_u64 v[120:121], v[50:51], 0, s[70:71]
	v_pk_fma_f32 v[126:127], v[82:83], v[116:117], v[126:127] op_sel_hi:[0,1,1]
	v_pk_fma_f32 v[130:131], v[82:83], v[122:123], v[130:131] op_sel_hi:[0,1,1]
	global_load_dwordx4 v[116:119], v[90:91], off offset:1024
	s_nop 0
	global_load_dwordx4 v[120:123], v[120:121], off offset:16
	s_mov_b64 s[70:71], 0x2800
	s_waitcnt vmcnt(0)
; template <int TYPE>
; __device__ __forceinline__ void lg_compute(const KArgs& a, unsigned char* wsb, int l, int h, int dir, const LgRaw& raw, LAS unsigned char* lds, int tid) {
;     ...
;         f32x4 z0 = *(const f32x4*)bs, z1 = *(const f32x4*)(bs + 4);
; #pragma unroll
;         for (int r = 0; r < 16; ++r) { z0 += ua[r] * *(const f32x4*)(up + r * 256); z1 += ua[r] * *(const f32x4*)(up + r * 256 + 4); }
	v_pk_fma_f32 v[128:129], v[80:81], v[118:119], v[128:129] op_sel_hi:[0,1,1]
	v_pk_fma_f32 v[126:127], v[80:81], v[116:117], v[126:127] op_sel_hi:[0,1,1]
	v_pk_fma_f32 v[130:131], v[80:81], v[122:123], v[130:131] op_sel_hi:[0,1,1]
	v_pk_fma_f32 v[80:81], v[80:81], v[120:121], v[124:125] op_sel_hi:[0,1,1]
	v_lshl_add_u64 v[120:121], v[50:51], 0, s[70:71]
	global_load_dwordx4 v[116:119], v[90:91], off offset:2048
	s_nop 0
	global_load_dwordx4 v[120:123], v[120:121], off offset:16
	s_mov_b64 s[70:71], 0x2c00
	s_waitcnt vmcnt(0)
	v_pk_fma_f32 v[126:127], v[78:79], v[116:117], v[126:127] op_sel_hi:[0,1,1]
	v_lshl_add_u64 v[116:117], v[50:51], 0, s[70:71]
	v_pk_fma_f32 v[124:125], v[78:79], v[118:119], v[128:129] op_sel_hi:[0,1,1]
	v_pk_fma_f32 v[120:121], v[78:79], v[120:121], v[80:81] op_sel_hi:[0,1,1]
	v_pk_fma_f32 v[122:123], v[78:79], v[122:123], v[130:131] op_sel_hi:[0,1,1]
	global_load_dwordx4 v[78:81], v[90:91], off offset:3072
	s_nop 0
	global_load_dwordx4 v[116:119], v[116:117], off offset:16
	s_mov_b64 s[70:71], 0x3000
	s_waitcnt vmcnt(0)
	v_pk_fma_f32 v[80:81], v[76:77], v[80:81], v[124:125] op_sel_hi:[0,1,1]
	v_pk_fma_f32 v[120:121], v[76:77], v[116:117], v[120:121] op_sel_hi:[0,1,1]
	v_lshl_add_u64 v[116:117], v[50:51], 0, s[70:71]
	s_movk_i32 s70, 0x3000
	v_add_co_u32_e32 v124, vcc, s70, v50
	v_pk_fma_f32 v[90:91], v[76:77], v[78:79], v[126:127] op_sel_hi:[0,1,1]
	s_nop 0
	v_addc_co_u32_e32 v125, vcc, 0, v51, vcc
	v_pk_fma_f32 v[122:123], v[76:77], v[118:119], v[122:123] op_sel_hi:[0,1,1]
	global_load_dwordx4 v[76:79], v[124:125], off
	s_nop 0
	global_load_dwordx4 v[116:119], v[116:117], off offset:16
	s_mov_b64 s[70:71], 0x3400
	s_waitcnt vmcnt(0)
	v_pk_fma_f32 v[80:81], v[48:49], v[78:79], v[80:81] op_sel_hi:[0,1,1]
	v_pk_fma_f32 v[120:121], v[48:49], v[116:117], v[120:121] op_sel_hi:[0,1,1]
	v_lshl_add_u64 v[116:117], v[50:51], 0, s[70:71]
	v_pk_fma_f32 v[90:91], v[48:49], v[76:77], v[90:91] op_sel_hi:[0,1,1]
	v_pk_fma_f32 v[48:49], v[48:49], v[118:119], v[122:123] op_sel_hi:[0,1,1]
	global_load_dwordx4 v[76:79], v[124:125], off offset:1024
	s_nop 0
	global_load_dwordx4 v[116:119], v[116:117], off offset:16
	s_mov_b64 s[70:71], 0x3800
	s_waitcnt vmcnt(0)
	v_pk_fma_f32 v[76:77], v[46:47], v[76:77], v[90:91] op_sel_hi:[0,1,1]
	v_pk_fma_f32 v[90:91], v[46:47], v[116:117], v[120:121] op_sel_hi:[0,1,1]
	v_lshl_add_u64 v[116:117], v[50:51], 0, s[70:71]
	v_pk_fma_f32 v[78:79], v[46:47], v[78:79], v[80:81] op_sel_hi:[0,1,1]
	v_pk_fma_f32 v[80:81], v[46:47], v[118:119], v[48:49] op_sel_hi:[0,1,1]
	global_load_dwordx4 v[46:49], v[124:125], off offset:2048
	s_nop 0
	global_load_dwordx4 v[116:119], v[116:117], off offset:16
	s_mov_b64 s[70:71], 0x3c00
	s_waitcnt vmcnt(0)
	v_pk_fma_f32 v[120:121], v[44:45], v[48:49], v[78:79] op_sel_hi:[0,1,1]
	v_lshl_add_u64 v[48:49], v[50:51], 0, s[70:71]
	v_pk_fma_f32 v[78:79], v[44:45], v[46:47], v[76:77] op_sel_hi:[0,1,1]
	v_pk_fma_f32 v[76:77], v[44:45], v[116:117], v[90:91] op_sel_hi:[0,1,1]
	v_pk_fma_f32 v[80:81], v[44:45], v[118:119], v[80:81] op_sel_hi:[0,1,1]
	global_load_dwordx4 v[44:47], v[124:125], off offset:3072
	s_nop 0
	global_load_dwordx4 v[48:51], v[48:49], off offset:16
	s_waitcnt vmcnt(0)
; #define LAS __attribute__((address_space(3)))
; __device__ __forceinline__ float logsigmoid_(float z) { return fminf(z, 0.f) - __logf(1.f + __expf(-fabsf(z))); }
; template <int TYPE>
; __device__ __forceinline__ void lg_compute(const KArgs& a, unsigned char* wsb, int l, int h, int dir, const LgRaw& raw, LAS unsigned char* lds, int tid) {
;     ...
;         f32x4 g0, g1;
; #pragma unroll
;         for (int e = 0; e < 4; ++e) { g0[e] = logsigmoid_(z0[e]) * (1.f / 16.f); g1[e] = logsigmoid_(z1[e]) * (1.f / 16.f); }
;         *(LAS f32x4*)(G + i * C::LDG + d8 * 8) = g0; *(LAS f32x4*)(G + i * C::LDG + d8 * 8 + 4) = g1;
;         *(LAS bf16x8*)(Kb + i * C::LDK_ + d8 * 8) = raw.k;
; template <int TYPE>
; __device__ __forceinline__ void cumsum_g(int dir, LAS unsigned char* lds, int tid) {
;     using C = Cfg<TYPE>; constexpr int NSEG = 512 / C::DK, SEGL = 64 / NSEG;
;     LAS float* G = (LAS float*)(lds + SC_G); LAS float* SG = (LAS float*)(lds + SC_SEG);
;     const int d = tid % C::DK, seg = tid / C::DK;
;     __syncthreads();
;     float run = 0.f;
; #pragma unroll
;     for (int ii = 0; ii < SEGL; ++ii) { const int i = seg * SEGL + (dir ? SEGL - 1 - ii : ii); run += G[i * C::LDG + d]; G[i * C::LDG + d] = run; }
;     SG[seg * 128 + d] = run;
;     __syncthreads();
	v_pk_fma_f32 v[78:79], v[74:75], v[44:45], v[78:79] op_sel_hi:[0,1,1]
	v_pk_fma_f32 v[46:47], v[74:75], v[46:47], v[120:121] op_sel_hi:[0,1,1]
	v_pk_fma_f32 v[44:45], v[74:75], v[50:51], v[80:81] op_sel_hi:[0,1,1]
	v_pk_fma_f32 v[74:75], v[74:75], v[48:49], v[76:77] op_sel_hi:[0,1,1]
	v_mul_f32_e64 v48, |v78|, s72
	v_exp_f32_e32 v48, v48
	v_min_f32_e32 v50, 0, v78
	v_min_f32_e32 v80, 0, v44
	v_mul_f32_e64 v44, |v44|, s72
	v_add_f32_e32 v48, 1.0, v48
	v_cmp_gt_f32_e32 vcc, s33, v48
	v_exp_f32_e32 v44, v44
	s_nop 0
	v_cndmask_b32_e64 v49, 0, 32, vcc
	v_ldexp_f32 v48, v48, v49
	v_log_f32_e32 v48, v48
	v_add_f32_e32 v44, 1.0, v44
	v_mul_f32_e32 v49, 0x3f317217, v48
	v_fma_f32 v49, v48, s92, -v49
	v_fmac_f32_e32 v49, 0x3377d1cf, v48
	v_fmac_f32_e32 v49, 0x3f317217, v48
	v_cmp_lt_f32_e64 s[70:71], |v48|, s9
	s_nop 1
	v_cndmask_b32_e64 v48, v48, v49, s[70:71]
	v_cndmask_b32_e32 v49, 0, v238, vcc
	v_sub_f32_e32 v76, v48, v49
	v_mul_f32_e64 v49, |v74|, s72
	v_exp_f32_e32 v49, v49
	v_min_f32_e32 v48, 0, v74
	v_add_f32_e32 v49, 1.0, v49
	v_cmp_gt_f32_e32 vcc, s33, v49
	s_nop 1
	v_cndmask_b32_e64 v51, 0, 32, vcc
	v_ldexp_f32 v49, v49, v51
	v_log_f32_e32 v49, v49
	s_nop 0
	v_mul_f32_e32 v51, 0x3f317217, v49
	v_fma_f32 v51, v49, s92, -v51
	v_fmac_f32_e32 v51, 0x3377d1cf, v49
	v_fmac_f32_e32 v51, 0x3f317217, v49
	v_cmp_lt_f32_e64 s[70:71], |v49|, s9
	s_nop 1
	v_cndmask_b32_e64 v49, v49, v51, s[70:71]
	v_cndmask_b32_e32 v51, 0, v238, vcc
	v_sub_f32_e32 v74, v49, v51
	v_mul_f32_e64 v49, |v79|, s72
	v_exp_f32_e32 v49, v49
	v_min_f32_e32 v51, 0, v79
	v_add_f32_e32 v49, 1.0, v49
	v_cmp_gt_f32_e32 vcc, s33, v49
	s_nop 1
	v_cndmask_b32_e64 v77, 0, 32, vcc
	v_ldexp_f32 v49, v49, v77
	v_log_f32_e32 v49, v49
	s_nop 0
	v_mul_f32_e32 v77, 0x3f317217, v49
	v_fma_f32 v77, v49, s92, -v77
	v_fmac_f32_e32 v77, 0x3377d1cf, v49
	v_fmac_f32_e32 v77, 0x3f317217, v49
	v_cmp_lt_f32_e64 s[70:71], |v49|, s9
	s_nop 1
	v_cndmask_b32_e64 v49, v49, v77, s[70:71]
	v_cndmask_b32_e32 v77, 0, v238, vcc
	v_sub_f32_e32 v77, v49, v77
	v_min_f32_e32 v49, 0, v75
	v_mul_f32_e64 v75, |v75|, s72
	v_exp_f32_e32 v75, v75
	v_pk_add_f32 v[50:51], v[50:51], v[76:77] neg_lo:[0,1] neg_hi:[0,1]
	v_add_f32_e32 v75, 1.0, v75
	v_cmp_gt_f32_e32 vcc, s33, v75
	v_pk_mul_f32 v[76:77], v[50:51], s[8:9] op_sel_hi:[1,0]
	s_nop 0
	v_cndmask_b32_e64 v78, 0, 32, vcc
	v_ldexp_f32 v75, v75, v78
	v_log_f32_e32 v75, v75
	s_nop 0
	v_mul_f32_e32 v78, 0x3f317217, v75
	v_fma_f32 v78, v75, s92, -v78
	v_fmac_f32_e32 v78, 0x3377d1cf, v75
	v_fmac_f32_e32 v78, 0x3f317217, v75
	v_cmp_lt_f32_e64 s[70:71], |v75|, s9
	s_nop 1
	v_cndmask_b32_e64 v75, v75, v78, s[70:71]
	v_cndmask_b32_e32 v78, 0, v238, vcc
	v_sub_f32_e32 v75, v75, v78
	v_min_f32_e32 v78, 0, v46
	v_mul_f32_e64 v46, |v46|, s72
	v_exp_f32_e32 v46, v46
	s_nop 0
	v_add_f32_e32 v46, 1.0, v46
	v_cmp_gt_f32_e32 vcc, s33, v46
	s_nop 1
	v_cndmask_b32_e64 v79, 0, 32, vcc
	v_ldexp_f32 v46, v46, v79
	v_log_f32_e32 v46, v46
	s_nop 0
	v_mul_f32_e32 v79, 0x3f317217, v46
	v_fma_f32 v79, v46, s92, -v79
	v_fmac_f32_e32 v79, 0x3377d1cf, v46
	v_fmac_f32_e32 v79, 0x3f317217, v46
	v_cmp_lt_f32_e64 s[70:71], |v46|, s9
	s_nop 1
	v_cndmask_b32_e64 v46, v46, v79, s[70:71]
	v_cndmask_b32_e32 v79, 0, v238, vcc
	v_cmp_gt_f32_e32 vcc, s33, v44
	v_sub_f32_e32 v46, v46, v79
	s_nop 0
	v_cndmask_b32_e64 v79, 0, 32, vcc
	v_ldexp_f32 v44, v44, v79
	v_log_f32_e32 v44, v44
	s_nop 0
	v_mul_f32_e32 v79, 0x3f317217, v44
	v_fma_f32 v79, v44, s92, -v79
	v_fmac_f32_e32 v79, 0x3377d1cf, v44
	v_fmac_f32_e32 v79, 0x3f317217, v44
	v_cmp_lt_f32_e64 s[70:71], |v44|, s9
	s_nop 1
	v_cndmask_b32_e64 v44, v44, v79, s[70:71]
	v_cndmask_b32_e32 v79, 0, v238, vcc
	v_sub_f32_e32 v44, v44, v79
	v_min_f32_e32 v79, 0, v47
	v_mul_f32_e64 v47, |v47|, s72
	v_exp_f32_e32 v47, v47
	s_nop 0
	v_add_f32_e32 v47, 1.0, v47
	v_cmp_gt_f32_e32 vcc, s33, v47
	s_nop 1
	v_cndmask_b32_e64 v81, 0, 32, vcc
	v_ldexp_f32 v47, v47, v81
	v_log_f32_e32 v47, v47
	s_nop 0
	v_mul_f32_e32 v81, 0x3f317217, v47
	v_fma_f32 v81, v47, s92, -v81
	v_fmac_f32_e32 v81, 0x3377d1cf, v47
	v_fmac_f32_e32 v81, 0x3f317217, v47
	v_cmp_lt_f32_e64 s[70:71], |v47|, s9
	s_nop 1
	v_cndmask_b32_e64 v47, v47, v81, s[70:71]
	v_cndmask_b32_e32 v81, 0, v238, vcc
	v_sub_f32_e32 v47, v47, v81
	v_min_f32_e32 v81, 0, v45
	v_mul_f32_e64 v45, |v45|, s72
	v_exp_f32_e32 v45, v45
	v_pk_add_f32 v[46:47], v[78:79], v[46:47] neg_lo:[0,1] neg_hi:[0,1]
	s_movk_i32 s72, 0x110
	v_pk_mul_f32 v[78:79], v[46:47], s[8:9] op_sel_hi:[1,0]
	v_add_f32_e32 v45, 1.0, v45
	v_cmp_gt_f32_e32 vcc, s33, v45
	s_nop 1
	v_cndmask_b32_e64 v46, 0, 32, vcc
	v_ldexp_f32 v45, v45, v46
	v_log_f32_e32 v45, v45
	s_nop 0
	v_mul_f32_e32 v46, 0x3f317217, v45
	v_fma_f32 v46, v45, s92, -v46
	v_fmac_f32_e32 v46, 0x3377d1cf, v45
	v_fmac_f32_e32 v46, 0x3f317217, v45
	v_cmp_lt_f32_e64 s[70:71], |v45|, s9
	s_nop 1
	v_cndmask_b32_e64 v45, v45, v46, s[70:71]
	v_cndmask_b32_e32 v46, 0, v238, vcc
	v_sub_f32_e32 v45, v45, v46
	v_pk_add_f32 v[46:47], v[48:49], v[74:75] neg_lo:[0,1] neg_hi:[0,1]
	v_pk_add_f32 v[48:49], v[80:81], v[44:45] neg_lo:[0,1] neg_hi:[0,1]
	v_pk_mul_f32 v[44:45], v[46:47], s[8:9] op_sel_hi:[1,0]
	v_pk_mul_f32 v[46:47], v[48:49], s[8:9] op_sel_hi:[1,0]
	ds_write_b128 v83, v[76:79]
	ds_write_b128 v83, v[44:47] offset:16
	ds_write_b128 v85, v[20:23] offset:33792
	v_or_b32_e32 v44, s76, v87
	v_mad_u64_u32 v[44:45], s[70:71], v44, s72, v[66:67]
	s_waitcnt lgkmcnt(0)
	s_barrier
	ds_read_b32 v158, v44
	v_or_b32_e32 v142, s93, v87
	v_mad_u64_u32 v[142:143], s[70:71], v142, s72, v[66:67]
	ds_read_b32 v159, v142
	s_movk_i32 s93, 0x110
	v_or_b32_e32 v144, s79, v87
	v_mad_u64_u32 v[144:145], s[70:71], v144, s72, v[66:67]
	ds_read_b32 v160, v144
	v_or_b32_e32 v146, s78, v87
	v_mad_u64_u32 v[146:147], s[70:71], v146, s72, v[66:67]
	ds_read_b32 v161, v146
	v_or_b32_e32 v148, s75, v87
	v_mad_u64_u32 v[148:149], s[70:71], v148, s72, v[66:67]
	ds_read_b32 v162, v148
	v_or_b32_e32 v150, s74, v87
	v_mad_u64_u32 v[150:151], s[70:71], v150, s72, v[66:67]
	ds_read_b32 v163, v150
	v_or_b32_e32 v152, s4, v87
	v_mad_u64_u32 v[152:153], s[70:71], v152, s72, v[66:67]
	ds_read_b32 v164, v152
	v_or_b32_e32 v154, s80, v87
	v_mad_u64_u32 v[154:155], s[70:71], v154, s72, v[66:67]
	ds_read_b32 v165, v154
	s_waitcnt lgkmcnt(0)
	v_add_f32_e32 v46, 0, v158
	ds_write_b32 v44, v46
	v_add_f32_e32 v46, v46, v159
	ds_write_b32 v142, v46
	v_add_f32_e32 v46, v46, v160
	ds_write_b32 v144, v46
	v_add_f32_e32 v46, v46, v161
	ds_write_b32 v146, v46
	v_add_f32_e32 v46, v46, v162
	ds_write_b32 v148, v46
	v_add_f32_e32 v46, v46, v163
	ds_write_b32 v150, v46
	v_add_f32_e32 v46, v46, v164
	ds_write_b32 v152, v46
	v_add_f32_e32 v45, v46, v165
	ds_write_b32 v154, v45


; template <int TYPE>
; __device__ __forceinline__ void cumsum_g(int dir, LAS unsigned char* lds, int tid) {
;     ...
;     for (int ii = 0; ii < SEGL; ++ii) { const int i = seg * SEGL + (dir ? SEGL - 1 - ii : ii); run += G[i * C::LDG + d]; G[i * C::LDG + d] = run; }
;     SG[seg * 128 + d] = run;
;     __syncthreads();
;     float off = 0.f;
; #pragma unroll
;     for (int s = 0; s < NSEG; ++s) { const bool before = dir ? (s > seg) : (s < seg); if (before) off += SG[s * 128 + d]; }
	ds_write_b32 v93, v45
	v_mov_b32_e32 v44, 0
	s_waitcnt lgkmcnt(0)
	s_barrier
	s_and_saveexec_b64 s[70:71], s[86:87]
	s_cbranch_execz .LBB0_517
	ds_read_b32 v44, v89
	s_waitcnt lgkmcnt(0)
	v_add_f32_e32 v44, 0, v44
